# P6 EpiYab epilogue rewritten (batched 16B loads, permlane16 pairing); P8/P12 rstd computed lane-parallel; sc1 stores in transposes; DT half; P2 epilogue
# speedup vs baseline: 1.0226x; 1.0122x over previous
; #define LAS __attribute__((address_space(3)))
; __device__ __forceinline__ unsigned pk2(float lo, float hi) { return pk2hw(lo, hi); }
; __device__ __forceinline__ void transpose_item(const float* W, int K, int N, bf16_t* WT, int drow0, LAS float* scr, int k0, int n0, int lane) {
;     ...
;     for (int i = 0; i < 32; ++i) { const int kk = 2 * i + (lane >> 5); scr[kk * 33 + (lane & 31)] = W[(size_t)(k0 + kk) * N + n0 + (lane & 31)]; }
;     asm volatile("s_waitcnt lgkmcnt(0)" ::: "memory");
;     const int c = lane & 7;
; #pragma unroll
;     for (int j = 0; j < 4; ++j) { const int n = (lane >> 3) + 8 * j; const LAS float* s = scr + (8 * c) * 33 + n;
;         u32x4 o; o.x = pk2(s[0 * 33], s[1 * 33]); o.y = pk2(s[2 * 33], s[3 * 33]); o.z = pk2(s[4 * 33], s[5 * 33]); o.w = pk2(s[6 * 33], s[7 * 33]);
;         *(u32x4*)(WT + (size_t)(drow0 + n) * K + k0 + 8 * c) = o; }
; __global__ void __launch_bounds__(NTHR, 2) fwd_kernel(Args a) {
;     ...
;         for (int it = gw; it < IT_IN; it += NGW) {
;             const int r = it, kb = r / 257, nb = r % 257, n0 = nb * 32; const int d0 = n0 < 3072 ? n0 : (n0 == 3072 ? 8192 : n0 - 32);
;             transpose_item(a.in[I_WIN], DM, INW, WinT, d0, scr, kb * 64, n0, lane);
;         }
.LBB0_22:
	s_lshl_b32 s12, s9, 1
	s_lshl_b32 s13, s8, 1
	v_or_b32_e32 v48, s12, v1
	v_or_b32_e32 v49, s13, v0
	s_add_i32 s14, s12, 4
	s_add_i32 s15, s13, 4
	s_add_i32 s16, s12, 8
	s_add_i32 s17, s13, 8
	s_add_i32 s18, s12, 12
	s_add_i32 s19, s13, 12
	s_add_i32 s20, s12, 16
	s_add_i32 s21, s13, 16
	s_add_i32 s22, s12, 20
	s_add_i32 s23, s13, 20
	s_add_i32 s24, s12, 24
	s_add_i32 s25, s13, 24
	s_add_i32 s12, s12, 28
	s_add_i32 s13, s13, 28
	v_add_u32_e32 v16, s0, v49
	v_or_b32_e32 v50, s14, v1
	v_or_b32_e32 v51, s15, v0
	v_or_b32_e32 v52, s16, v1
	v_or_b32_e32 v53, s17, v0
	v_or_b32_e32 v54, s18, v1
	v_or_b32_e32 v55, s19, v0
	v_or_b32_e32 v56, s20, v1
	v_or_b32_e32 v57, s21, v0
	v_or_b32_e32 v58, s22, v1
	v_or_b32_e32 v59, s23, v0
	v_or_b32_e32 v60, s24, v1
	v_or_b32_e32 v61, s25, v0
	v_or_b32_e32 v62, s12, v1
	v_or_b32_e32 v63, s13, v0
	v_add_u32_e32 v18, s3, v48
	v_mad_i64_i32 v[16:17], s[12:13], v16, s6, v[8:9]
	v_add_u32_e32 v22, s3, v50
	v_add_u32_e32 v20, s0, v51
	v_add_u32_e32 v26, s3, v52
	v_add_u32_e32 v24, s0, v53
	v_add_u32_e32 v30, s3, v54
	v_add_u32_e32 v28, s0, v55
	v_add_u32_e32 v34, s3, v56
	v_add_u32_e32 v32, s0, v57
	v_add_u32_e32 v38, s3, v58
	v_add_u32_e32 v36, s0, v59
	v_add_u32_e32 v42, s3, v60
	v_add_u32_e32 v40, s0, v61
	v_add_u32_e32 v46, s3, v62
	v_add_u32_e32 v44, s0, v63
	v_mad_i64_i32 v[18:19], s[12:13], v18, s6, v[8:9]
	v_mad_i64_i32 v[20:21], s[12:13], v20, s6, v[8:9]
	v_mad_i64_i32 v[22:23], s[12:13], v22, s6, v[8:9]
	v_mad_i64_i32 v[24:25], s[12:13], v24, s6, v[8:9]
	v_mad_i64_i32 v[26:27], s[12:13], v26, s6, v[8:9]
	v_mad_i64_i32 v[28:29], s[12:13], v28, s6, v[8:9]
	v_mad_i64_i32 v[30:31], s[12:13], v30, s6, v[8:9]
	v_mad_i64_i32 v[32:33], s[12:13], v32, s6, v[8:9]
	v_mad_i64_i32 v[34:35], s[12:13], v34, s6, v[8:9]
	v_mad_i64_i32 v[36:37], s[12:13], v36, s6, v[8:9]
	v_mad_i64_i32 v[38:39], s[12:13], v38, s6, v[8:9]
	v_mad_i64_i32 v[40:41], s[12:13], v40, s6, v[8:9]
	v_mad_i64_i32 v[42:43], s[12:13], v42, s6, v[8:9]
	v_mad_i64_i32 v[44:45], s[12:13], v44, s6, v[8:9]
	v_mad_i64_i32 v[46:47], s[12:13], v46, s6, v[8:9]
	global_load_dword v64, v[16:17], off
	global_load_dword v65, v[18:19], off
	global_load_dword v66, v[20:21], off
	global_load_dword v67, v[22:23], off
	global_load_dword v68, v[24:25], off
	global_load_dword v69, v[26:27], off
	global_load_dword v70, v[28:29], off
	global_load_dword v71, v[30:31], off
	global_load_dword v72, v[32:33], off
	global_load_dword v73, v[34:35], off
	global_load_dword v74, v[36:37], off
	global_load_dword v75, v[38:39], off
	global_load_dword v76, v[40:41], off
	global_load_dword v77, v[42:43], off
	global_load_dword v78, v[44:45], off
	global_load_dword v79, v[46:47], off
	s_add_i32 s8, s8, 16
	s_add_i32 s9, s9, 16
	s_add_i32 s7, s7, -16
	v_mad_u64_u32 v[16:17], s[12:13], v49, s5, v[4:5]
	s_cmp_lg_u32 s7, 0
	v_mad_u64_u32 v[18:19], s[12:13], v48, s5, v[4:5]
	v_mad_u64_u32 v[20:21], s[12:13], v51, s5, v[4:5]
	v_mad_u64_u32 v[22:23], s[12:13], v50, s5, v[4:5]
	v_mad_u64_u32 v[24:25], s[12:13], v53, s5, v[4:5]
	v_mad_u64_u32 v[26:27], s[12:13], v52, s5, v[4:5]
	v_mad_u64_u32 v[28:29], s[12:13], v55, s5, v[4:5]
	v_mad_u64_u32 v[30:31], s[12:13], v54, s5, v[4:5]
	v_mad_u64_u32 v[32:33], s[12:13], v57, s5, v[4:5]
	v_mad_u64_u32 v[34:35], s[12:13], v56, s5, v[4:5]
	v_mad_u64_u32 v[36:37], s[12:13], v59, s5, v[4:5]
	v_mad_u64_u32 v[38:39], s[12:13], v58, s5, v[4:5]
	v_mad_u64_u32 v[40:41], s[12:13], v61, s5, v[4:5]
	v_mad_u64_u32 v[42:43], s[12:13], v60, s5, v[4:5]
	v_mad_u64_u32 v[44:45], s[12:13], v63, s5, v[4:5]
	v_mad_u64_u32 v[46:47], s[12:13], v62, s5, v[4:5]
	s_waitcnt vmcnt(15)
	ds_write_b32 v16, v64
	s_waitcnt vmcnt(14)
	ds_write_b32 v18, v65
	s_waitcnt vmcnt(13)
	ds_write_b32 v20, v66
	s_waitcnt vmcnt(12)
	ds_write_b32 v22, v67
	s_waitcnt vmcnt(11)
	ds_write_b32 v24, v68
	s_waitcnt vmcnt(10)
	ds_write_b32 v26, v69
	s_waitcnt vmcnt(9)
	ds_write_b32 v28, v70
	s_waitcnt vmcnt(8)
	ds_write_b32 v30, v71
	s_waitcnt vmcnt(7)
	ds_write_b32 v32, v72
	s_waitcnt vmcnt(6)
	ds_write_b32 v34, v73
	s_waitcnt vmcnt(5)
	ds_write_b32 v36, v74
	s_waitcnt vmcnt(4)
	ds_write_b32 v38, v75
	s_waitcnt vmcnt(3)
	ds_write_b32 v40, v76
	s_waitcnt vmcnt(2)
	ds_write_b32 v42, v77
	s_waitcnt vmcnt(1)
	ds_write_b32 v44, v78
	s_waitcnt vmcnt(0)
	ds_write_b32 v46, v79
	s_cbranch_scc1 .LBB0_22
	s_sub_i32 s3, s2, 32
	s_cmpk_lg_i32 s1, 0x60
	s_waitcnt lgkmcnt(0)
	s_cselect_b32 s3, s3, 0x2000
	s_cmpk_lt_i32 s1, 0x60
	ds_read2_b32 v[8:9], v12 offset0:33 offset1:41
	ds_read2_b32 v[20:21], v12 offset1:8
	ds_read2_b32 v[22:23], v12 offset0:66 offset1:74
	ds_read2_b32 v[24:25], v12 offset0:99 offset1:107
	ds_read2_b32 v[26:27], v12 offset0:132 offset1:140
	ds_read2_b32 v[28:29], v12 offset0:165 offset1:173
	ds_read2_b32 v[30:31], v12 offset0:198 offset1:206
	ds_read2_b32 v[32:33], v12 offset0:231 offset1:239
	s_cselect_b32 s2, s2, s3
	v_or_b32_e32 v36, s2, v11
	s_ashr_i32 s1, s0, 31
	v_ashrrev_i32_e32 v37, 31, v36
	v_lshl_add_u64 v[34:35], s[0:1], 1, v[6:7]
	v_lshlrev_b64 v[36:37], 12, v[36:37]
	s_waitcnt lgkmcnt(6)
	v_cvt_pk_bf16_f32 v16, v20, v8
	s_waitcnt lgkmcnt(4)
	v_cvt_pk_bf16_f32 v17, v22, v24
	s_waitcnt lgkmcnt(2)
	v_cvt_pk_bf16_f32 v18, v26, v28
	s_waitcnt lgkmcnt(0)
	v_cvt_pk_bf16_f32 v19, v30, v32
	v_lshl_add_u64 v[36:37], v[34:35], 0, v[36:37]
	v_or_b32_e32 v8, s2, v13
	global_store_dwordx4 v[36:37], v[16:19], off sc1
	s_add_i32 s4, s4, s70
	s_cmpk_gt_i32 s4, 0x201f
	v_cvt_pk_bf16_f32 v16, v21, v9
	v_ashrrev_i32_e32 v9, 31, v8
	v_cvt_pk_bf16_f32 v17, v23, v25
	v_cvt_pk_bf16_f32 v18, v27, v29
	v_cvt_pk_bf16_f32 v19, v31, v33
	v_lshlrev_b64 v[8:9], 12, v[8:9]
	ds_read2_b32 v[20:21], v12 offset0:49 offset1:57
	ds_read2_b32 v[22:23], v12 offset0:16 offset1:24
	ds_read2_b32 v[24:25], v12 offset0:82 offset1:90
	ds_read2_b32 v[26:27], v12 offset0:115 offset1:123
	ds_read2_b32 v[28:29], v12 offset0:148 offset1:156
	ds_read2_b32 v[30:31], v12 offset0:181 offset1:189
	ds_read2_b32 v[32:33], v12 offset0:214 offset1:222
	ds_read2_b32 v[36:37], v12 offset0:247 offset1:255
	v_lshl_add_u64 v[8:9], v[34:35], 0, v[8:9]
	global_store_dwordx4 v[8:9], v[16:19], off sc1
	v_or_b32_e32 v8, s2, v14
	v_ashrrev_i32_e32 v9, 31, v8
	v_lshlrev_b64 v[8:9], 12, v[8:9]
	s_waitcnt lgkmcnt(6)
	v_cvt_pk_bf16_f32 v16, v22, v20
	s_waitcnt lgkmcnt(4)
	v_cvt_pk_bf16_f32 v17, v24, v26
	s_waitcnt lgkmcnt(2)
	v_cvt_pk_bf16_f32 v18, v28, v30
	s_waitcnt lgkmcnt(0)
	v_cvt_pk_bf16_f32 v19, v32, v36
	v_lshl_add_u64 v[8:9], v[34:35], 0, v[8:9]
	global_store_dwordx4 v[8:9], v[16:19], off sc1
	v_or_b32_e32 v8, s2, v15
	v_ashrrev_i32_e32 v9, 31, v8
	v_lshlrev_b64 v[8:9], 12, v[8:9]
	v_cvt_pk_bf16_f32 v16, v23, v21
	v_cvt_pk_bf16_f32 v17, v25, v27
	v_cvt_pk_bf16_f32 v18, v29, v31
	v_cvt_pk_bf16_f32 v19, v33, v37
	v_lshl_add_u64 v[8:9], v[34:35], 0, v[8:9]
	global_store_dwordx4 v[8:9], v[16:19], off sc1
	s_waitcnt lgkmcnt(0)
	s_cbranch_scc0 .LBB0_21

; __global__ void __launch_bounds__(NTHR, 2) fwd_kernel(Args a) {
;     ...
;         for (int i = gtid; i < 224 * 256; i += NT) ((u32x4*)(WinT + (size_t)8224 * DM))[i] = (u32x4){0u, 0u, 0u, 0u};
.LBB0_26:
	v_add_u32_e32 v5, s0, v5
	v_cmp_lt_i32_e32 vcc, s1, v5
	global_store_dwordx4 v[6:7], v[0:3], off sc1
	s_or_b64 s[6:7], vcc, s[6:7]
	v_lshl_add_u64 v[6:7], v[6:7], 0, s[4:5]
	s_andn2_b64 exec, exec, s[6:7]
	s_cbranch_execnz .LBB0_26

; __device__ __forceinline__ unsigned pk2(float lo, float hi) { return pk2hw(lo, hi); }
; __global__ void __launch_bounds__(NTHR, 2) fwd_kernel(Args a) {
;     ...
;         for (int gi = gtid; gi < 2048 * 512; gi += NT) {
;             const int k1 = gi >> 9, j0 = (gi & 511) * 8; float v[8];
; #pragma unroll
;             for (int e = 0; e < 8; ++e) { const int j = j0 + e; const int ph = (k1 * (j & 2047)) & 2047; const float x = (float)ph * (1.0f / 1024.0f); v[e] = j < 2048 ? cospif(x) : -sinpif(x); }
;             u32x4 o; o.x = pk2(v[0], v[1]); o.y = pk2(v[2], v[3]); o.z = pk2(v[4], v[5]); o.w = pk2(v[6], v[7]);
;             *(u32x4*)(DT + (size_t)k1 * 4096 + j0) = o;
.LBB0_29:
	s_or_b64 exec, exec, s[4:5]
	v_cvt_pk_bf16_f32 v12, v3, v12
	v_ashrrev_i32_e32 v3, 31, v2
	v_lshlrev_b64 v[2:3], 13, v[2:3]
	v_add_u32_e32 v11, s0, v11
	v_lshl_add_u64 v[2:3], s[72:73], 0, v[2:3]
	v_lshlrev_b32_e32 v0, 1, v0
	v_cmp_lt_i32_e32 vcc, s17, v11
	v_cvt_pk_bf16_f32 v13, v13, v14
	v_cvt_pk_bf16_f32 v14, v15, v16
	v_cvt_pk_bf16_f32 v15, v17, v22
	v_lshl_add_u64 v[2:3], v[2:3], 0, v[0:1]
	s_or_b64 s[8:9], vcc, s[8:9]
	v_add_u32_e32 v5, s1, v5
	global_store_dwordx4 v[2:3], v[12:15], off sc1
	s_andn2_b64 exec, exec, s[8:9]
	s_cbranch_execz .LBB0_62

; __device__ __forceinline__ unsigned pk2(float lo, float hi) { return pk2hw(lo, hi); }
; __global__ void __launch_bounds__(NTHR, 2) fwd_kernel(Args a) {
;     ...
;         for (int gi = gtid; gi < 512 * 32; gi += NT) {
;             const int m = gi >> 5, c0 = (gi & 31) * 8; float v[8];
; #pragma unroll
;             for (int e = 0; e < 8; ++e) { const int ph = ((m & 255) * (c0 + e)) & 255; const float x = (float)ph * (1.0f / 128.0f); v[e] = (m < 256 ? cospif(x) : sinpif(x)) * 0.0625f; }
;             u32x4 o; o.x = pk2(v[0], v[1]); o.y = pk2(v[2], v[3]); o.z = pk2(v[4], v[5]); o.w = pk2(v[6], v[7]);
;             *(u32x4*)(CS + (size_t)m * 256 + c0) = o;
.LBB0_64:
	s_or_b64 exec, exec, s[2:3]
	v_mul_f32_e32 v20, 0x3d800000, v20
	v_cmp_lg_f32_e32 vcc, s15, v19
	v_mul_f32_e32 v18, 0x3d800000, v18
	v_mul_f32_e32 v16, 0x3d800000, v16
	v_cndmask_b32_e32 v19, v8, v20, vcc
	v_cmp_lg_f32_e32 vcc, s15, v17
	v_mul_f32_e32 v14, 0x3d800000, v14
	v_mul_f32_e32 v12, 0x3d800000, v12
	v_cndmask_b32_e32 v17, v8, v18, vcc
	v_cmp_lg_f32_e32 vcc, s15, v15
	v_mul_f32_e32 v10, 0x3d800000, v10
	v_mul_f32_e32 v3, 0x3d800000, v3
	v_cndmask_b32_e32 v15, v8, v16, vcc
	v_cmp_lg_f32_e32 vcc, s15, v13
	v_add_u32_e32 v4, s0, v4
	s_nop 0
	v_cndmask_b32_e32 v13, v8, v14, vcc
	v_cmp_lg_f32_e32 vcc, s15, v11
	v_and_b32_e32 v14, 0xf8, v5
	v_add_u32_e32 v5, s1, v5
	v_cndmask_b32_e32 v11, v8, v12, vcc
	v_cmp_lg_f32_e32 vcc, s15, v9
	v_cvt_pk_bf16_f32 v11, v11, v13
	v_cvt_pk_bf16_f32 v12, v15, v17
	v_cndmask_b32_e32 v9, v8, v10, vcc
	v_cmp_lg_f32_e32 vcc, s15, v0
	s_nop 1
	v_cndmask_b32_e32 v0, v8, v3, vcc
	v_mul_f32_e32 v3, 0x3d800000, v22
	v_cmp_lg_f32_e32 vcc, s15, v21
	v_cvt_pk_bf16_f32 v10, v0, v9
	v_lshlrev_b32_e32 v0, 1, v14
	v_cndmask_b32_e32 v3, v8, v3, vcc
	v_cvt_pk_bf16_f32 v13, v19, v3
	v_ashrrev_i32_e32 v3, 31, v2
	v_lshlrev_b64 v[2:3], 9, v[2:3]
	v_lshl_add_u64 v[2:3], s[6:7], 0, v[2:3]
	v_cmp_lt_i32_e32 vcc, s17, v4
	v_lshl_add_u64 v[2:3], v[2:3], 0, v[0:1]
	s_or_b64 s[8:9], vcc, s[8:9]
	global_store_dwordx4 v[2:3], v[10:13], off sc1
	s_andn2_b64 exec, exec, s[8:9]
	s_cbranch_execz .LBB0_97

; template <class Epi, class Sched, bool DEFER>
; __device__ __forceinline__ void gemm_fast_core(LAS unsigned char* lds, const GemmP g, const Sched& S, const Epi& E, f32x4 (&acc)[2][2][4][2], Unit& cur) {
;     ...
;             const int row0 = cur.pm * BM + wr * 64 + fr, col0 = cur.pn * BM + wc * 32 + 4 * fq;
; #pragma unroll
;             for (int ai = 0; ai < 2; ++ai)
; #pragma unroll
;                 for (int m = 0; m < 4; ++m)
; #pragma unroll
;                     for (int bj = 0; bj < 2; ++bj)
; #pragma unroll
;                         for (int n = 0; n < 2; ++n) E.put(cur, row0 + ai * HALF + m * 16, col0 + bj * HALF + n * 16, acc[ai][bj][m][n]);
.LBB0_1413:
	v_lshl_add_u32 v238, s26, 8, v148
	v_lshlrev_b32_e32 v238, 11, v238
	v_bfe_u32 v239, v150, 2, 2
	v_and_b32_e32 v240, 1, v239
	v_lshrrev_b32_e32 v239, 1, v239
	v_lshlrev_b32_e32 v240, 4, v240
	v_lshl_add_u32 v240, v239, 3, v240
	v_and_b32_e32 v239, 0x60, v150
	v_add_u32_e32 v240, v240, v239
	v_lshl_add_u32 v240, s4, 8, v240
	v_add_lshl_u32 v238, v238, v240, 1
	v_mov_b32_e32 v240, v238
	v_add_u32_e32 v241, 0x10000, v238
	v_add_u32_e32 v242, 0x20000, v238
	v_add_u32_e32 v243, 0x30000, v238
	v_add_u32_e32 v244, 0x80000, v238
	v_add_u32_e32 v245, 0x90000, v238
	v_add_u32_e32 v246, 0xa0000, v238
	v_add_u32_e32 v247, 0xb0000, v238
	s_and_b64 vcc, exec, s[28:29]
	s_cbranch_vccnz .Lp6e_bz1
	global_load_dwordx4 v[154:157], v240, s[92:93]
	global_load_dwordx4 v[158:161], v240, s[92:93] offset:256
	global_load_dwordx4 v[162:165], v241, s[92:93]
	global_load_dwordx4 v[166:169], v241, s[92:93] offset:256
	global_load_dwordx4 v[170:173], v242, s[92:93]
	global_load_dwordx4 v[174:177], v242, s[92:93] offset:256
	global_load_dwordx4 v[178:181], v243, s[92:93]
	global_load_dwordx4 v[182:185], v243, s[92:93] offset:256
	global_load_dwordx4 v[190:193], v244, s[92:93]
	global_load_dwordx4 v[194:197], v244, s[92:93] offset:256
	global_load_dwordx4 v[198:201], v245, s[92:93]
	global_load_dwordx4 v[202:205], v245, s[92:93] offset:256
	global_load_dwordx4 v[206:209], v246, s[92:93]
	global_load_dwordx4 v[210:213], v246, s[92:93] offset:256
	global_load_dwordx4 v[214:217], v247, s[92:93]
	global_load_dwordx4 v[230:233], v247, s[92:93] offset:256
	s_waitcnt vmcnt(15)
	v_permlane16_swap_b32_e32 v154, v156
	v_permlane16_swap_b32_e32 v155, v157
	v_lshlrev_b32_e32 v136, 16, v154
	v_and_b32_e32 v137, 0xffff0000, v154
	v_lshlrev_b32_e32 v138, 16, v155
	v_and_b32_e32 v139, 0xffff0000, v155
	v_lshlrev_b32_e32 v140, 16, v156
	v_and_b32_e32 v141, 0xffff0000, v156
	v_lshlrev_b32_e32 v142, 16, v157
	v_and_b32_e32 v143, 0xffff0000, v157
	v_pk_mul_f32 v[124:125], v[124:125], v[136:137]
	v_pk_mul_f32 v[126:127], v[126:127], v[138:139]
	v_pk_mul_f32 v[120:121], v[120:121], v[140:141]
	v_pk_mul_f32 v[122:123], v[122:123], v[142:143]
	s_nop 0
	v_cvt_pk_bf16_f32 v124, v124, v125
	v_cvt_pk_bf16_f32 v125, v126, v127
	v_cvt_pk_bf16_f32 v126, v120, v121
	v_cvt_pk_bf16_f32 v127, v122, v123
	s_nop 1
	v_permlane16_swap_b32_e32 v124, v126
	v_permlane16_swap_b32_e32 v125, v127
	global_store_dwordx4 v240, v[124:127], s[64:65]
	s_waitcnt vmcnt(15)
	v_permlane16_swap_b32_e32 v158, v160
	v_permlane16_swap_b32_e32 v159, v161
	v_lshlrev_b32_e32 v136, 16, v158
	v_and_b32_e32 v137, 0xffff0000, v158
	v_lshlrev_b32_e32 v138, 16, v159
	v_and_b32_e32 v139, 0xffff0000, v159
	v_lshlrev_b32_e32 v140, 16, v160
	v_and_b32_e32 v141, 0xffff0000, v160
	v_lshlrev_b32_e32 v142, 16, v161
	v_and_b32_e32 v143, 0xffff0000, v161
	v_pk_mul_f32 v[116:117], v[116:117], v[136:137]
	v_pk_mul_f32 v[118:119], v[118:119], v[138:139]
	v_pk_mul_f32 v[112:113], v[112:113], v[140:141]
	v_pk_mul_f32 v[114:115], v[114:115], v[142:143]
	s_nop 0
	v_cvt_pk_bf16_f32 v116, v116, v117
	v_cvt_pk_bf16_f32 v117, v118, v119
	v_cvt_pk_bf16_f32 v118, v112, v113
	v_cvt_pk_bf16_f32 v119, v114, v115
	s_nop 1
	v_permlane16_swap_b32_e32 v116, v118
	v_permlane16_swap_b32_e32 v117, v119
	global_store_dwordx4 v240, v[116:119], s[64:65] offset:256
	s_waitcnt vmcnt(15)
	v_permlane16_swap_b32_e32 v162, v164
	v_permlane16_swap_b32_e32 v163, v165
	v_lshlrev_b32_e32 v136, 16, v162
	v_and_b32_e32 v137, 0xffff0000, v162
	v_lshlrev_b32_e32 v138, 16, v163
	v_and_b32_e32 v139, 0xffff0000, v163
	v_lshlrev_b32_e32 v140, 16, v164
	v_and_b32_e32 v141, 0xffff0000, v164
	v_lshlrev_b32_e32 v142, 16, v165
	v_and_b32_e32 v143, 0xffff0000, v165
	v_pk_mul_f32 v[108:109], v[108:109], v[136:137]
	v_pk_mul_f32 v[110:111], v[110:111], v[138:139]
	v_pk_mul_f32 v[104:105], v[104:105], v[140:141]
	v_pk_mul_f32 v[106:107], v[106:107], v[142:143]
	s_nop 0
	v_cvt_pk_bf16_f32 v108, v108, v109
	v_cvt_pk_bf16_f32 v109, v110, v111
	v_cvt_pk_bf16_f32 v110, v104, v105
	v_cvt_pk_bf16_f32 v111, v106, v107
	s_nop 1
	v_permlane16_swap_b32_e32 v108, v110
	v_permlane16_swap_b32_e32 v109, v111
	global_store_dwordx4 v241, v[108:111], s[64:65]
	s_waitcnt vmcnt(15)
	v_permlane16_swap_b32_e32 v166, v168
	v_permlane16_swap_b32_e32 v167, v169
	v_lshlrev_b32_e32 v136, 16, v166
	v_and_b32_e32 v137, 0xffff0000, v166
	v_lshlrev_b32_e32 v138, 16, v167
	v_and_b32_e32 v139, 0xffff0000, v167
	v_lshlrev_b32_e32 v140, 16, v168
	v_and_b32_e32 v141, 0xffff0000, v168
	v_lshlrev_b32_e32 v142, 16, v169
	v_and_b32_e32 v143, 0xffff0000, v169
	v_pk_mul_f32 v[100:101], v[100:101], v[136:137]
	v_pk_mul_f32 v[102:103], v[102:103], v[138:139]
	v_pk_mul_f32 v[96:97], v[96:97], v[140:141]
	v_pk_mul_f32 v[98:99], v[98:99], v[142:143]
	s_nop 0
	v_cvt_pk_bf16_f32 v100, v100, v101
	v_cvt_pk_bf16_f32 v101, v102, v103
	v_cvt_pk_bf16_f32 v102, v96, v97
	v_cvt_pk_bf16_f32 v103, v98, v99
	s_nop 1
	v_permlane16_swap_b32_e32 v100, v102
	v_permlane16_swap_b32_e32 v101, v103
	global_store_dwordx4 v241, v[100:103], s[64:65] offset:256
	s_waitcnt vmcnt(15)
	v_permlane16_swap_b32_e32 v170, v172
	v_permlane16_swap_b32_e32 v171, v173
	v_lshlrev_b32_e32 v136, 16, v170
	v_and_b32_e32 v137, 0xffff0000, v170
	v_lshlrev_b32_e32 v138, 16, v171
	v_and_b32_e32 v139, 0xffff0000, v171
	v_lshlrev_b32_e32 v140, 16, v172
	v_and_b32_e32 v141, 0xffff0000, v172
	v_lshlrev_b32_e32 v142, 16, v173
	v_and_b32_e32 v143, 0xffff0000, v173
	v_pk_mul_f32 v[92:93], v[92:93], v[136:137]
	v_pk_mul_f32 v[94:95], v[94:95], v[138:139]
	v_pk_mul_f32 v[88:89], v[88:89], v[140:141]
	v_pk_mul_f32 v[90:91], v[90:91], v[142:143]
	s_nop 0
	v_cvt_pk_bf16_f32 v92, v92, v93
	v_cvt_pk_bf16_f32 v93, v94, v95
	v_cvt_pk_bf16_f32 v94, v88, v89
	v_cvt_pk_bf16_f32 v95, v90, v91
	s_nop 1
	v_permlane16_swap_b32_e32 v92, v94
	v_permlane16_swap_b32_e32 v93, v95
	global_store_dwordx4 v242, v[92:95], s[64:65]
	s_waitcnt vmcnt(15)
; template <class Epi, class Sched, bool DEFER>
; __device__ __forceinline__ void gemm_fast_core(LAS unsigned char* lds, const GemmP g, const Sched& S, const Epi& E, f32x4 (&acc)[2][2][4][2], Unit& cur) {
;     ...
;             const int row0 = cur.pm * BM + wr * 64 + fr, col0 = cur.pn * BM + wc * 32 + 4 * fq;
; #pragma unroll
;             for (int ai = 0; ai < 2; ++ai)
; #pragma unroll
;                 for (int m = 0; m < 4; ++m)
; #pragma unroll
;                     for (int bj = 0; bj < 2; ++bj)
; #pragma unroll
;                         for (int n = 0; n < 2; ++n) E.put(cur, row0 + ai * HALF + m * 16, col0 + bj * HALF + n * 16, acc[ai][bj][m][n]);
	v_permlane16_swap_b32_e32 v174, v176
	v_permlane16_swap_b32_e32 v175, v177
	v_lshlrev_b32_e32 v136, 16, v174
	v_and_b32_e32 v137, 0xffff0000, v174
	v_lshlrev_b32_e32 v138, 16, v175
	v_and_b32_e32 v139, 0xffff0000, v175
	v_lshlrev_b32_e32 v140, 16, v176
	v_and_b32_e32 v141, 0xffff0000, v176
	v_lshlrev_b32_e32 v142, 16, v177
	v_and_b32_e32 v143, 0xffff0000, v177
	v_pk_mul_f32 v[84:85], v[84:85], v[136:137]
	v_pk_mul_f32 v[86:87], v[86:87], v[138:139]
	v_pk_mul_f32 v[80:81], v[80:81], v[140:141]
	v_pk_mul_f32 v[82:83], v[82:83], v[142:143]
	s_nop 0
	v_cvt_pk_bf16_f32 v84, v84, v85
	v_cvt_pk_bf16_f32 v85, v86, v87
	v_cvt_pk_bf16_f32 v86, v80, v81
	v_cvt_pk_bf16_f32 v87, v82, v83
	s_nop 1
	v_permlane16_swap_b32_e32 v84, v86
	v_permlane16_swap_b32_e32 v85, v87
	global_store_dwordx4 v242, v[84:87], s[64:65] offset:256
	s_waitcnt vmcnt(15)
	v_permlane16_swap_b32_e32 v178, v180
	v_permlane16_swap_b32_e32 v179, v181
	v_lshlrev_b32_e32 v136, 16, v178
	v_and_b32_e32 v137, 0xffff0000, v178
	v_lshlrev_b32_e32 v138, 16, v179
	v_and_b32_e32 v139, 0xffff0000, v179
	v_lshlrev_b32_e32 v140, 16, v180
	v_and_b32_e32 v141, 0xffff0000, v180
	v_lshlrev_b32_e32 v142, 16, v181
	v_and_b32_e32 v143, 0xffff0000, v181
	v_pk_mul_f32 v[76:77], v[76:77], v[136:137]
	v_pk_mul_f32 v[78:79], v[78:79], v[138:139]
	v_pk_mul_f32 v[72:73], v[72:73], v[140:141]
	v_pk_mul_f32 v[74:75], v[74:75], v[142:143]
	s_nop 0
	v_cvt_pk_bf16_f32 v76, v76, v77
	v_cvt_pk_bf16_f32 v77, v78, v79
	v_cvt_pk_bf16_f32 v78, v72, v73
	v_cvt_pk_bf16_f32 v79, v74, v75
	s_nop 1
	v_permlane16_swap_b32_e32 v76, v78
	v_permlane16_swap_b32_e32 v77, v79
	global_store_dwordx4 v243, v[76:79], s[64:65]
	s_waitcnt vmcnt(15)
	v_permlane16_swap_b32_e32 v182, v184
	v_permlane16_swap_b32_e32 v183, v185
	v_lshlrev_b32_e32 v136, 16, v182
	v_and_b32_e32 v137, 0xffff0000, v182
	v_lshlrev_b32_e32 v138, 16, v183
	v_and_b32_e32 v139, 0xffff0000, v183
	v_lshlrev_b32_e32 v140, 16, v184
	v_and_b32_e32 v141, 0xffff0000, v184
	v_lshlrev_b32_e32 v142, 16, v185
	v_and_b32_e32 v143, 0xffff0000, v185
	v_pk_mul_f32 v[68:69], v[68:69], v[136:137]
	v_pk_mul_f32 v[70:71], v[70:71], v[138:139]
	v_pk_mul_f32 v[64:65], v[64:65], v[140:141]
	v_pk_mul_f32 v[66:67], v[66:67], v[142:143]
	s_nop 0
	v_cvt_pk_bf16_f32 v68, v68, v69
	v_cvt_pk_bf16_f32 v69, v70, v71
	v_cvt_pk_bf16_f32 v70, v64, v65
	v_cvt_pk_bf16_f32 v71, v66, v67
	s_nop 1
	v_permlane16_swap_b32_e32 v68, v70
	v_permlane16_swap_b32_e32 v69, v71
	global_store_dwordx4 v243, v[68:71], s[64:65] offset:256
	s_waitcnt vmcnt(15)
	v_permlane16_swap_b32_e32 v190, v192
	v_permlane16_swap_b32_e32 v191, v193
	v_lshlrev_b32_e32 v136, 16, v190
	v_and_b32_e32 v137, 0xffff0000, v190
	v_lshlrev_b32_e32 v138, 16, v191
	v_and_b32_e32 v139, 0xffff0000, v191
	v_lshlrev_b32_e32 v140, 16, v192
	v_and_b32_e32 v141, 0xffff0000, v192
	v_lshlrev_b32_e32 v142, 16, v193
	v_and_b32_e32 v143, 0xffff0000, v193
	v_pk_mul_f32 v[60:61], v[60:61], v[136:137]
	v_pk_mul_f32 v[62:63], v[62:63], v[138:139]
	v_pk_mul_f32 v[56:57], v[56:57], v[140:141]
	v_pk_mul_f32 v[58:59], v[58:59], v[142:143]
	s_nop 0
	v_cvt_pk_bf16_f32 v60, v60, v61
	v_cvt_pk_bf16_f32 v61, v62, v63
	v_cvt_pk_bf16_f32 v62, v56, v57
	v_cvt_pk_bf16_f32 v63, v58, v59
	s_nop 1
	v_permlane16_swap_b32_e32 v60, v62
	v_permlane16_swap_b32_e32 v61, v63
	global_store_dwordx4 v244, v[60:63], s[64:65]
	s_waitcnt vmcnt(15)
	v_permlane16_swap_b32_e32 v194, v196
	v_permlane16_swap_b32_e32 v195, v197
	v_lshlrev_b32_e32 v136, 16, v194
	v_and_b32_e32 v137, 0xffff0000, v194
	v_lshlrev_b32_e32 v138, 16, v195
	v_and_b32_e32 v139, 0xffff0000, v195
	v_lshlrev_b32_e32 v140, 16, v196
	v_and_b32_e32 v141, 0xffff0000, v196
	v_lshlrev_b32_e32 v142, 16, v197
	v_and_b32_e32 v143, 0xffff0000, v197
	v_pk_mul_f32 v[52:53], v[52:53], v[136:137]
	v_pk_mul_f32 v[54:55], v[54:55], v[138:139]
	v_pk_mul_f32 v[48:49], v[48:49], v[140:141]
	v_pk_mul_f32 v[50:51], v[50:51], v[142:143]
	s_nop 0
	v_cvt_pk_bf16_f32 v52, v52, v53
	v_cvt_pk_bf16_f32 v53, v54, v55
	v_cvt_pk_bf16_f32 v54, v48, v49
	v_cvt_pk_bf16_f32 v55, v50, v51
	s_nop 1
	v_permlane16_swap_b32_e32 v52, v54
	v_permlane16_swap_b32_e32 v53, v55
	global_store_dwordx4 v244, v[52:55], s[64:65] offset:256
	s_waitcnt vmcnt(15)
	v_permlane16_swap_b32_e32 v198, v200
	v_permlane16_swap_b32_e32 v199, v201
	v_lshlrev_b32_e32 v136, 16, v198
	v_and_b32_e32 v137, 0xffff0000, v198
	v_lshlrev_b32_e32 v138, 16, v199
	v_and_b32_e32 v139, 0xffff0000, v199
	v_lshlrev_b32_e32 v140, 16, v200
	v_and_b32_e32 v141, 0xffff0000, v200
	v_lshlrev_b32_e32 v142, 16, v201
	v_and_b32_e32 v143, 0xffff0000, v201
	v_pk_mul_f32 v[44:45], v[44:45], v[136:137]
	v_pk_mul_f32 v[46:47], v[46:47], v[138:139]
	v_pk_mul_f32 v[40:41], v[40:41], v[140:141]
	v_pk_mul_f32 v[42:43], v[42:43], v[142:143]
	s_nop 0
	v_cvt_pk_bf16_f32 v44, v44, v45
	v_cvt_pk_bf16_f32 v45, v46, v47
	v_cvt_pk_bf16_f32 v46, v40, v41
	v_cvt_pk_bf16_f32 v47, v42, v43
	s_nop 1
	v_permlane16_swap_b32_e32 v44, v46
	v_permlane16_swap_b32_e32 v45, v47
	global_store_dwordx4 v245, v[44:47], s[64:65]
	s_waitcnt vmcnt(15)
	v_permlane16_swap_b32_e32 v202, v204
	v_permlane16_swap_b32_e32 v203, v205
	v_lshlrev_b32_e32 v136, 16, v202
	v_and_b32_e32 v137, 0xffff0000, v202
	v_lshlrev_b32_e32 v138, 16, v203
	v_and_b32_e32 v139, 0xffff0000, v203
	v_lshlrev_b32_e32 v140, 16, v204
	v_and_b32_e32 v141, 0xffff0000, v204
	v_lshlrev_b32_e32 v142, 16, v205
	v_and_b32_e32 v143, 0xffff0000, v205
	v_pk_mul_f32 v[36:37], v[36:37], v[136:137]
	v_pk_mul_f32 v[38:39], v[38:39], v[138:139]
	v_pk_mul_f32 v[32:33], v[32:33], v[140:141]
	v_pk_mul_f32 v[34:35], v[34:35], v[142:143]
	s_nop 0
	v_cvt_pk_bf16_f32 v36, v36, v37
	v_cvt_pk_bf16_f32 v37, v38, v39
	v_cvt_pk_bf16_f32 v38, v32, v33
	v_cvt_pk_bf16_f32 v39, v34, v35
	s_nop 1
	v_permlane16_swap_b32_e32 v36, v38
	v_permlane16_swap_b32_e32 v37, v39
	global_store_dwordx4 v245, v[36:39], s[64:65] offset:256
	s_waitcnt vmcnt(15)
; template <class Epi, class Sched, bool DEFER>
; __device__ __forceinline__ void gemm_fast_core(LAS unsigned char* lds, const GemmP g, const Sched& S, const Epi& E, f32x4 (&acc)[2][2][4][2], Unit& cur) {
;     ...
;             const int row0 = cur.pm * BM + wr * 64 + fr, col0 = cur.pn * BM + wc * 32 + 4 * fq;
; #pragma unroll
;             for (int ai = 0; ai < 2; ++ai)
; #pragma unroll
;                 for (int m = 0; m < 4; ++m)
; #pragma unroll
;                     for (int bj = 0; bj < 2; ++bj)
; #pragma unroll
;                         for (int n = 0; n < 2; ++n) E.put(cur, row0 + ai * HALF + m * 16, col0 + bj * HALF + n * 16, acc[ai][bj][m][n]);
	v_permlane16_swap_b32_e32 v206, v208
	v_permlane16_swap_b32_e32 v207, v209
	v_lshlrev_b32_e32 v136, 16, v206
	v_and_b32_e32 v137, 0xffff0000, v206
	v_lshlrev_b32_e32 v138, 16, v207
	v_and_b32_e32 v139, 0xffff0000, v207
	v_lshlrev_b32_e32 v140, 16, v208
	v_and_b32_e32 v141, 0xffff0000, v208
	v_lshlrev_b32_e32 v142, 16, v209
	v_and_b32_e32 v143, 0xffff0000, v209
	v_pk_mul_f32 v[28:29], v[28:29], v[136:137]
	v_pk_mul_f32 v[30:31], v[30:31], v[138:139]
	v_pk_mul_f32 v[24:25], v[24:25], v[140:141]
	v_pk_mul_f32 v[26:27], v[26:27], v[142:143]
	s_nop 0
	v_cvt_pk_bf16_f32 v28, v28, v29
	v_cvt_pk_bf16_f32 v29, v30, v31
	v_cvt_pk_bf16_f32 v30, v24, v25
	v_cvt_pk_bf16_f32 v31, v26, v27
	s_nop 1
	v_permlane16_swap_b32_e32 v28, v30
	v_permlane16_swap_b32_e32 v29, v31
	global_store_dwordx4 v246, v[28:31], s[64:65]
	s_waitcnt vmcnt(15)
	v_permlane16_swap_b32_e32 v210, v212
	v_permlane16_swap_b32_e32 v211, v213
	v_lshlrev_b32_e32 v136, 16, v210
	v_and_b32_e32 v137, 0xffff0000, v210
	v_lshlrev_b32_e32 v138, 16, v211
	v_and_b32_e32 v139, 0xffff0000, v211
	v_lshlrev_b32_e32 v140, 16, v212
	v_and_b32_e32 v141, 0xffff0000, v212
	v_lshlrev_b32_e32 v142, 16, v213
	v_and_b32_e32 v143, 0xffff0000, v213
	v_pk_mul_f32 v[20:21], v[20:21], v[136:137]
	v_pk_mul_f32 v[22:23], v[22:23], v[138:139]
	v_pk_mul_f32 v[16:17], v[16:17], v[140:141]
	v_pk_mul_f32 v[18:19], v[18:19], v[142:143]
	s_nop 0
	v_cvt_pk_bf16_f32 v20, v20, v21
	v_cvt_pk_bf16_f32 v21, v22, v23
	v_cvt_pk_bf16_f32 v22, v16, v17
	v_cvt_pk_bf16_f32 v23, v18, v19
	s_nop 1
	v_permlane16_swap_b32_e32 v20, v22
	v_permlane16_swap_b32_e32 v21, v23
	global_store_dwordx4 v246, v[20:23], s[64:65] offset:256
	s_waitcnt vmcnt(15)
	v_permlane16_swap_b32_e32 v214, v216
	v_permlane16_swap_b32_e32 v215, v217
	v_lshlrev_b32_e32 v136, 16, v214
	v_and_b32_e32 v137, 0xffff0000, v214
	v_lshlrev_b32_e32 v138, 16, v215
	v_and_b32_e32 v139, 0xffff0000, v215
	v_lshlrev_b32_e32 v140, 16, v216
	v_and_b32_e32 v141, 0xffff0000, v216
	v_lshlrev_b32_e32 v142, 16, v217
	v_and_b32_e32 v143, 0xffff0000, v217
	v_pk_mul_f32 v[12:13], v[12:13], v[136:137]
	v_pk_mul_f32 v[14:15], v[14:15], v[138:139]
	v_pk_mul_f32 v[8:9], v[8:9], v[140:141]
	v_pk_mul_f32 v[10:11], v[10:11], v[142:143]
	s_nop 0
	v_cvt_pk_bf16_f32 v12, v12, v13
	v_cvt_pk_bf16_f32 v13, v14, v15
	v_cvt_pk_bf16_f32 v14, v8, v9
	v_cvt_pk_bf16_f32 v15, v10, v11
	s_nop 1
	v_permlane16_swap_b32_e32 v12, v14
	v_permlane16_swap_b32_e32 v13, v15
	global_store_dwordx4 v247, v[12:15], s[64:65]
	s_waitcnt vmcnt(15)
	v_permlane16_swap_b32_e32 v230, v232
	v_permlane16_swap_b32_e32 v231, v233
	v_lshlrev_b32_e32 v136, 16, v230
	v_and_b32_e32 v137, 0xffff0000, v230
	v_lshlrev_b32_e32 v138, 16, v231
	v_and_b32_e32 v139, 0xffff0000, v231
	v_lshlrev_b32_e32 v140, 16, v232
	v_and_b32_e32 v141, 0xffff0000, v232
	v_lshlrev_b32_e32 v142, 16, v233
	v_and_b32_e32 v143, 0xffff0000, v233
	v_pk_mul_f32 v[4:5], v[4:5], v[136:137]
	v_pk_mul_f32 v[6:7], v[6:7], v[138:139]
	v_pk_mul_f32 v[0:1], v[0:1], v[140:141]
	v_pk_mul_f32 v[2:3], v[2:3], v[142:143]
	s_nop 0
	v_cvt_pk_bf16_f32 v4, v4, v5
	v_cvt_pk_bf16_f32 v5, v6, v7
	v_cvt_pk_bf16_f32 v6, v0, v1
	v_cvt_pk_bf16_f32 v7, v2, v3
	s_nop 1
	v_permlane16_swap_b32_e32 v4, v6
	v_permlane16_swap_b32_e32 v5, v7
	global_store_dwordx4 v247, v[4:7], s[64:65] offset:256
	s_branch .Lp6e_done
.Lp6e_bz1:
	global_load_dwordx4 v[154:157], v240, s[64:65]
	global_load_dwordx4 v[190:193], v240, s[94:95]
	global_load_dwordx4 v[158:161], v240, s[64:65] offset:256
	global_load_dwordx4 v[194:197], v240, s[94:95] offset:256
	global_load_dwordx4 v[162:165], v241, s[64:65]
	global_load_dwordx4 v[198:201], v241, s[94:95]
	global_load_dwordx4 v[166:169], v241, s[64:65] offset:256
	global_load_dwordx4 v[202:205], v241, s[94:95] offset:256
	global_load_dwordx4 v[170:173], v242, s[64:65]
	global_load_dwordx4 v[206:209], v242, s[94:95]
	global_load_dwordx4 v[174:177], v242, s[64:65] offset:256
	global_load_dwordx4 v[210:213], v242, s[94:95] offset:256
	global_load_dwordx4 v[178:181], v243, s[64:65]
	global_load_dwordx4 v[214:217], v243, s[94:95]
	global_load_dwordx4 v[182:185], v243, s[64:65] offset:256
	global_load_dwordx4 v[230:233], v243, s[94:95] offset:256
	s_waitcnt vmcnt(14)
	v_permlane16_swap_b32_e32 v154, v156
	v_permlane16_swap_b32_e32 v155, v157
	v_permlane16_swap_b32_e32 v190, v192
	v_permlane16_swap_b32_e32 v191, v193
	v_lshlrev_b32_e32 v136, 16, v154
	v_and_b32_e32 v137, 0xffff0000, v154
	v_lshlrev_b32_e32 v138, 16, v155
	v_and_b32_e32 v139, 0xffff0000, v155
	v_lshlrev_b32_e32 v140, 16, v156
	v_and_b32_e32 v141, 0xffff0000, v156
	v_lshlrev_b32_e32 v142, 16, v157
	v_and_b32_e32 v143, 0xffff0000, v157
	v_lshlrev_b32_e32 v144, 16, v190
	v_and_b32_e32 v145, 0xffff0000, v190
	v_lshlrev_b32_e32 v146, 16, v191
	v_and_b32_e32 v147, 0xffff0000, v191
	v_lshlrev_b32_e32 v234, 16, v192
	v_and_b32_e32 v235, 0xffff0000, v192
	v_lshlrev_b32_e32 v236, 16, v193
	v_and_b32_e32 v237, 0xffff0000, v193
	global_load_dwordx4 v[154:157], v244, s[64:65]
	global_load_dwordx4 v[190:193], v244, s[94:95]
	v_pk_fma_f32 v[124:125], v[124:125], v[144:145], v[136:137]
	v_pk_fma_f32 v[126:127], v[126:127], v[146:147], v[138:139]
	v_pk_fma_f32 v[120:121], v[120:121], v[234:235], v[140:141]
	v_pk_fma_f32 v[122:123], v[122:123], v[236:237], v[142:143]
	s_nop 0
	v_cvt_pk_bf16_f32 v124, v124, v125
	v_cvt_pk_bf16_f32 v125, v126, v127
	v_cvt_pk_bf16_f32 v126, v120, v121
	v_cvt_pk_bf16_f32 v127, v122, v123
	s_nop 1
	v_permlane16_swap_b32_e32 v124, v126
	v_permlane16_swap_b32_e32 v125, v127
	global_store_dwordx4 v240, v[124:127], s[90:91]
	s_waitcnt vmcnt(15)
; template <class Epi, class Sched, bool DEFER>
; __device__ __forceinline__ void gemm_fast_core(LAS unsigned char* lds, const GemmP g, const Sched& S, const Epi& E, f32x4 (&acc)[2][2][4][2], Unit& cur) {
;     ...
;             const int row0 = cur.pm * BM + wr * 64 + fr, col0 = cur.pn * BM + wc * 32 + 4 * fq;
; #pragma unroll
;             for (int ai = 0; ai < 2; ++ai)
; #pragma unroll
;                 for (int m = 0; m < 4; ++m)
; #pragma unroll
;                     for (int bj = 0; bj < 2; ++bj)
; #pragma unroll
;                         for (int n = 0; n < 2; ++n) E.put(cur, row0 + ai * HALF + m * 16, col0 + bj * HALF + n * 16, acc[ai][bj][m][n]);
	v_permlane16_swap_b32_e32 v158, v160
	v_permlane16_swap_b32_e32 v159, v161
	v_permlane16_swap_b32_e32 v194, v196
	v_permlane16_swap_b32_e32 v195, v197
	v_lshlrev_b32_e32 v136, 16, v158
	v_and_b32_e32 v137, 0xffff0000, v158
	v_lshlrev_b32_e32 v138, 16, v159
	v_and_b32_e32 v139, 0xffff0000, v159
	v_lshlrev_b32_e32 v140, 16, v160
	v_and_b32_e32 v141, 0xffff0000, v160
	v_lshlrev_b32_e32 v142, 16, v161
	v_and_b32_e32 v143, 0xffff0000, v161
	v_lshlrev_b32_e32 v144, 16, v194
	v_and_b32_e32 v145, 0xffff0000, v194
	v_lshlrev_b32_e32 v146, 16, v195
	v_and_b32_e32 v147, 0xffff0000, v195
	v_lshlrev_b32_e32 v234, 16, v196
	v_and_b32_e32 v235, 0xffff0000, v196
	v_lshlrev_b32_e32 v236, 16, v197
	v_and_b32_e32 v237, 0xffff0000, v197
	global_load_dwordx4 v[158:161], v244, s[64:65] offset:256
	global_load_dwordx4 v[194:197], v244, s[94:95] offset:256
	v_pk_fma_f32 v[116:117], v[116:117], v[144:145], v[136:137]
	v_pk_fma_f32 v[118:119], v[118:119], v[146:147], v[138:139]
	v_pk_fma_f32 v[112:113], v[112:113], v[234:235], v[140:141]
	v_pk_fma_f32 v[114:115], v[114:115], v[236:237], v[142:143]
	s_nop 0
	v_cvt_pk_bf16_f32 v116, v116, v117
	v_cvt_pk_bf16_f32 v117, v118, v119
	v_cvt_pk_bf16_f32 v118, v112, v113
	v_cvt_pk_bf16_f32 v119, v114, v115
	s_nop 1
	v_permlane16_swap_b32_e32 v116, v118
	v_permlane16_swap_b32_e32 v117, v119
	global_store_dwordx4 v240, v[116:119], s[90:91] offset:256
	s_waitcnt vmcnt(16)
	v_permlane16_swap_b32_e32 v162, v164
	v_permlane16_swap_b32_e32 v163, v165
	v_permlane16_swap_b32_e32 v198, v200
	v_permlane16_swap_b32_e32 v199, v201
	v_lshlrev_b32_e32 v136, 16, v162
	v_and_b32_e32 v137, 0xffff0000, v162
	v_lshlrev_b32_e32 v138, 16, v163
	v_and_b32_e32 v139, 0xffff0000, v163
	v_lshlrev_b32_e32 v140, 16, v164
	v_and_b32_e32 v141, 0xffff0000, v164
	v_lshlrev_b32_e32 v142, 16, v165
	v_and_b32_e32 v143, 0xffff0000, v165
	v_lshlrev_b32_e32 v144, 16, v198
	v_and_b32_e32 v145, 0xffff0000, v198
	v_lshlrev_b32_e32 v146, 16, v199
	v_and_b32_e32 v147, 0xffff0000, v199
	v_lshlrev_b32_e32 v234, 16, v200
	v_and_b32_e32 v235, 0xffff0000, v200
	v_lshlrev_b32_e32 v236, 16, v201
	v_and_b32_e32 v237, 0xffff0000, v201
	global_load_dwordx4 v[162:165], v245, s[64:65]
	global_load_dwordx4 v[198:201], v245, s[94:95]
	v_pk_fma_f32 v[108:109], v[108:109], v[144:145], v[136:137]
	v_pk_fma_f32 v[110:111], v[110:111], v[146:147], v[138:139]
	v_pk_fma_f32 v[104:105], v[104:105], v[234:235], v[140:141]
	v_pk_fma_f32 v[106:107], v[106:107], v[236:237], v[142:143]
	s_nop 0
	v_cvt_pk_bf16_f32 v108, v108, v109
	v_cvt_pk_bf16_f32 v109, v110, v111
	v_cvt_pk_bf16_f32 v110, v104, v105
	v_cvt_pk_bf16_f32 v111, v106, v107
	s_nop 1
	v_permlane16_swap_b32_e32 v108, v110
	v_permlane16_swap_b32_e32 v109, v111
	global_store_dwordx4 v241, v[108:111], s[90:91]
	s_waitcnt vmcnt(17)
	v_permlane16_swap_b32_e32 v166, v168
	v_permlane16_swap_b32_e32 v167, v169
	v_permlane16_swap_b32_e32 v202, v204
	v_permlane16_swap_b32_e32 v203, v205
	v_lshlrev_b32_e32 v136, 16, v166
	v_and_b32_e32 v137, 0xffff0000, v166
	v_lshlrev_b32_e32 v138, 16, v167
	v_and_b32_e32 v139, 0xffff0000, v167
	v_lshlrev_b32_e32 v140, 16, v168
	v_and_b32_e32 v141, 0xffff0000, v168
	v_lshlrev_b32_e32 v142, 16, v169
	v_and_b32_e32 v143, 0xffff0000, v169
	v_lshlrev_b32_e32 v144, 16, v202
	v_and_b32_e32 v145, 0xffff0000, v202
	v_lshlrev_b32_e32 v146, 16, v203
	v_and_b32_e32 v147, 0xffff0000, v203
	v_lshlrev_b32_e32 v234, 16, v204
	v_and_b32_e32 v235, 0xffff0000, v204
	v_lshlrev_b32_e32 v236, 16, v205
	v_and_b32_e32 v237, 0xffff0000, v205
	global_load_dwordx4 v[166:169], v245, s[64:65] offset:256
	global_load_dwordx4 v[202:205], v245, s[94:95] offset:256
	v_pk_fma_f32 v[100:101], v[100:101], v[144:145], v[136:137]
	v_pk_fma_f32 v[102:103], v[102:103], v[146:147], v[138:139]
	v_pk_fma_f32 v[96:97], v[96:97], v[234:235], v[140:141]
	v_pk_fma_f32 v[98:99], v[98:99], v[236:237], v[142:143]
	s_nop 0
	v_cvt_pk_bf16_f32 v100, v100, v101
	v_cvt_pk_bf16_f32 v101, v102, v103
	v_cvt_pk_bf16_f32 v102, v96, v97
	v_cvt_pk_bf16_f32 v103, v98, v99
	s_nop 1
	v_permlane16_swap_b32_e32 v100, v102
	v_permlane16_swap_b32_e32 v101, v103
	global_store_dwordx4 v241, v[100:103], s[90:91] offset:256
	s_waitcnt vmcnt(18)
	v_permlane16_swap_b32_e32 v170, v172
	v_permlane16_swap_b32_e32 v171, v173
	v_permlane16_swap_b32_e32 v206, v208
	v_permlane16_swap_b32_e32 v207, v209
	v_lshlrev_b32_e32 v136, 16, v170
	v_and_b32_e32 v137, 0xffff0000, v170
	v_lshlrev_b32_e32 v138, 16, v171
	v_and_b32_e32 v139, 0xffff0000, v171
	v_lshlrev_b32_e32 v140, 16, v172
	v_and_b32_e32 v141, 0xffff0000, v172
	v_lshlrev_b32_e32 v142, 16, v173
	v_and_b32_e32 v143, 0xffff0000, v173
	v_lshlrev_b32_e32 v144, 16, v206
	v_and_b32_e32 v145, 0xffff0000, v206
	v_lshlrev_b32_e32 v146, 16, v207
	v_and_b32_e32 v147, 0xffff0000, v207
	v_lshlrev_b32_e32 v234, 16, v208
	v_and_b32_e32 v235, 0xffff0000, v208
	v_lshlrev_b32_e32 v236, 16, v209
	v_and_b32_e32 v237, 0xffff0000, v209
	global_load_dwordx4 v[170:173], v246, s[64:65]
	global_load_dwordx4 v[206:209], v246, s[94:95]
	v_pk_fma_f32 v[92:93], v[92:93], v[144:145], v[136:137]
	v_pk_fma_f32 v[94:95], v[94:95], v[146:147], v[138:139]
	v_pk_fma_f32 v[88:89], v[88:89], v[234:235], v[140:141]
	v_pk_fma_f32 v[90:91], v[90:91], v[236:237], v[142:143]
	s_nop 0
	v_cvt_pk_bf16_f32 v92, v92, v93
	v_cvt_pk_bf16_f32 v93, v94, v95
	v_cvt_pk_bf16_f32 v94, v88, v89
	v_cvt_pk_bf16_f32 v95, v90, v91
	s_nop 1
	v_permlane16_swap_b32_e32 v92, v94
	v_permlane16_swap_b32_e32 v93, v95
	global_store_dwordx4 v242, v[92:95], s[90:91]
	s_waitcnt vmcnt(19)
; template <class Epi, class Sched, bool DEFER>
; __device__ __forceinline__ void gemm_fast_core(LAS unsigned char* lds, const GemmP g, const Sched& S, const Epi& E, f32x4 (&acc)[2][2][4][2], Unit& cur) {
;     ...
;             const int row0 = cur.pm * BM + wr * 64 + fr, col0 = cur.pn * BM + wc * 32 + 4 * fq;
; #pragma unroll
;             for (int ai = 0; ai < 2; ++ai)
; #pragma unroll
;                 for (int m = 0; m < 4; ++m)
; #pragma unroll
;                     for (int bj = 0; bj < 2; ++bj)
; #pragma unroll
;                         for (int n = 0; n < 2; ++n) E.put(cur, row0 + ai * HALF + m * 16, col0 + bj * HALF + n * 16, acc[ai][bj][m][n]);
	v_permlane16_swap_b32_e32 v174, v176
	v_permlane16_swap_b32_e32 v175, v177
	v_permlane16_swap_b32_e32 v210, v212
	v_permlane16_swap_b32_e32 v211, v213
	v_lshlrev_b32_e32 v136, 16, v174
	v_and_b32_e32 v137, 0xffff0000, v174
	v_lshlrev_b32_e32 v138, 16, v175
	v_and_b32_e32 v139, 0xffff0000, v175
	v_lshlrev_b32_e32 v140, 16, v176
	v_and_b32_e32 v141, 0xffff0000, v176
	v_lshlrev_b32_e32 v142, 16, v177
	v_and_b32_e32 v143, 0xffff0000, v177
	v_lshlrev_b32_e32 v144, 16, v210
	v_and_b32_e32 v145, 0xffff0000, v210
	v_lshlrev_b32_e32 v146, 16, v211
	v_and_b32_e32 v147, 0xffff0000, v211
	v_lshlrev_b32_e32 v234, 16, v212
	v_and_b32_e32 v235, 0xffff0000, v212
	v_lshlrev_b32_e32 v236, 16, v213
	v_and_b32_e32 v237, 0xffff0000, v213
	global_load_dwordx4 v[174:177], v246, s[64:65] offset:256
	global_load_dwordx4 v[210:213], v246, s[94:95] offset:256
	v_pk_fma_f32 v[84:85], v[84:85], v[144:145], v[136:137]
	v_pk_fma_f32 v[86:87], v[86:87], v[146:147], v[138:139]
	v_pk_fma_f32 v[80:81], v[80:81], v[234:235], v[140:141]
	v_pk_fma_f32 v[82:83], v[82:83], v[236:237], v[142:143]
	s_nop 0
	v_cvt_pk_bf16_f32 v84, v84, v85
	v_cvt_pk_bf16_f32 v85, v86, v87
	v_cvt_pk_bf16_f32 v86, v80, v81
	v_cvt_pk_bf16_f32 v87, v82, v83
	s_nop 1
	v_permlane16_swap_b32_e32 v84, v86
	v_permlane16_swap_b32_e32 v85, v87
	global_store_dwordx4 v242, v[84:87], s[90:91] offset:256
	s_waitcnt vmcnt(20)
	v_permlane16_swap_b32_e32 v178, v180
	v_permlane16_swap_b32_e32 v179, v181
	v_permlane16_swap_b32_e32 v214, v216
	v_permlane16_swap_b32_e32 v215, v217
	v_lshlrev_b32_e32 v136, 16, v178
	v_and_b32_e32 v137, 0xffff0000, v178
	v_lshlrev_b32_e32 v138, 16, v179
	v_and_b32_e32 v139, 0xffff0000, v179
	v_lshlrev_b32_e32 v140, 16, v180
	v_and_b32_e32 v141, 0xffff0000, v180
	v_lshlrev_b32_e32 v142, 16, v181
	v_and_b32_e32 v143, 0xffff0000, v181
	v_lshlrev_b32_e32 v144, 16, v214
	v_and_b32_e32 v145, 0xffff0000, v214
	v_lshlrev_b32_e32 v146, 16, v215
	v_and_b32_e32 v147, 0xffff0000, v215
	v_lshlrev_b32_e32 v234, 16, v216
	v_and_b32_e32 v235, 0xffff0000, v216
	v_lshlrev_b32_e32 v236, 16, v217
	v_and_b32_e32 v237, 0xffff0000, v217
	global_load_dwordx4 v[178:181], v247, s[64:65]
	global_load_dwordx4 v[214:217], v247, s[94:95]
	v_pk_fma_f32 v[76:77], v[76:77], v[144:145], v[136:137]
	v_pk_fma_f32 v[78:79], v[78:79], v[146:147], v[138:139]
	v_pk_fma_f32 v[72:73], v[72:73], v[234:235], v[140:141]
	v_pk_fma_f32 v[74:75], v[74:75], v[236:237], v[142:143]
	s_nop 0
	v_cvt_pk_bf16_f32 v76, v76, v77
	v_cvt_pk_bf16_f32 v77, v78, v79
	v_cvt_pk_bf16_f32 v78, v72, v73
	v_cvt_pk_bf16_f32 v79, v74, v75
	s_nop 1
	v_permlane16_swap_b32_e32 v76, v78
	v_permlane16_swap_b32_e32 v77, v79
	global_store_dwordx4 v243, v[76:79], s[90:91]
	s_waitcnt vmcnt(21)
	v_permlane16_swap_b32_e32 v182, v184
	v_permlane16_swap_b32_e32 v183, v185
	v_permlane16_swap_b32_e32 v230, v232
	v_permlane16_swap_b32_e32 v231, v233
	v_lshlrev_b32_e32 v136, 16, v182
	v_and_b32_e32 v137, 0xffff0000, v182
	v_lshlrev_b32_e32 v138, 16, v183
	v_and_b32_e32 v139, 0xffff0000, v183
	v_lshlrev_b32_e32 v140, 16, v184
	v_and_b32_e32 v141, 0xffff0000, v184
	v_lshlrev_b32_e32 v142, 16, v185
	v_and_b32_e32 v143, 0xffff0000, v185
	v_lshlrev_b32_e32 v144, 16, v230
	v_and_b32_e32 v145, 0xffff0000, v230
	v_lshlrev_b32_e32 v146, 16, v231
	v_and_b32_e32 v147, 0xffff0000, v231
	v_lshlrev_b32_e32 v234, 16, v232
	v_and_b32_e32 v235, 0xffff0000, v232
	v_lshlrev_b32_e32 v236, 16, v233
	v_and_b32_e32 v237, 0xffff0000, v233
	global_load_dwordx4 v[182:185], v247, s[64:65] offset:256
	global_load_dwordx4 v[230:233], v247, s[94:95] offset:256
	v_pk_fma_f32 v[68:69], v[68:69], v[144:145], v[136:137]
	v_pk_fma_f32 v[70:71], v[70:71], v[146:147], v[138:139]
	v_pk_fma_f32 v[64:65], v[64:65], v[234:235], v[140:141]
	v_pk_fma_f32 v[66:67], v[66:67], v[236:237], v[142:143]
	s_nop 0
	v_cvt_pk_bf16_f32 v68, v68, v69
	v_cvt_pk_bf16_f32 v69, v70, v71
	v_cvt_pk_bf16_f32 v70, v64, v65
	v_cvt_pk_bf16_f32 v71, v66, v67
	s_nop 1
	v_permlane16_swap_b32_e32 v68, v70
	v_permlane16_swap_b32_e32 v69, v71
	global_store_dwordx4 v243, v[68:71], s[90:91] offset:256
	s_waitcnt vmcnt(22)
	v_permlane16_swap_b32_e32 v154, v156
	v_permlane16_swap_b32_e32 v155, v157
	v_permlane16_swap_b32_e32 v190, v192
	v_permlane16_swap_b32_e32 v191, v193
	v_lshlrev_b32_e32 v136, 16, v154
	v_and_b32_e32 v137, 0xffff0000, v154
	v_lshlrev_b32_e32 v138, 16, v155
	v_and_b32_e32 v139, 0xffff0000, v155
	v_lshlrev_b32_e32 v140, 16, v156
	v_and_b32_e32 v141, 0xffff0000, v156
	v_lshlrev_b32_e32 v142, 16, v157
	v_and_b32_e32 v143, 0xffff0000, v157
	v_lshlrev_b32_e32 v144, 16, v190
	v_and_b32_e32 v145, 0xffff0000, v190
	v_lshlrev_b32_e32 v146, 16, v191
	v_and_b32_e32 v147, 0xffff0000, v191
	v_lshlrev_b32_e32 v234, 16, v192
	v_and_b32_e32 v235, 0xffff0000, v192
	v_lshlrev_b32_e32 v236, 16, v193
	v_and_b32_e32 v237, 0xffff0000, v193
	v_pk_fma_f32 v[60:61], v[60:61], v[144:145], v[136:137]
	v_pk_fma_f32 v[62:63], v[62:63], v[146:147], v[138:139]
	v_pk_fma_f32 v[56:57], v[56:57], v[234:235], v[140:141]
	v_pk_fma_f32 v[58:59], v[58:59], v[236:237], v[142:143]
	s_nop 0
	v_cvt_pk_bf16_f32 v60, v60, v61
	v_cvt_pk_bf16_f32 v61, v62, v63
	v_cvt_pk_bf16_f32 v62, v56, v57
	v_cvt_pk_bf16_f32 v63, v58, v59
	s_nop 1
	v_permlane16_swap_b32_e32 v60, v62
	v_permlane16_swap_b32_e32 v61, v63
	global_store_dwordx4 v244, v[60:63], s[90:91]
	s_waitcnt vmcnt(20)
; template <class Epi, class Sched, bool DEFER>
; __device__ __forceinline__ void gemm_fast_core(LAS unsigned char* lds, const GemmP g, const Sched& S, const Epi& E, f32x4 (&acc)[2][2][4][2], Unit& cur) {
;     ...
;             const int row0 = cur.pm * BM + wr * 64 + fr, col0 = cur.pn * BM + wc * 32 + 4 * fq;
; #pragma unroll
;             for (int ai = 0; ai < 2; ++ai)
; #pragma unroll
;                 for (int m = 0; m < 4; ++m)
; #pragma unroll
;                     for (int bj = 0; bj < 2; ++bj)
; #pragma unroll
;                         for (int n = 0; n < 2; ++n) E.put(cur, row0 + ai * HALF + m * 16, col0 + bj * HALF + n * 16, acc[ai][bj][m][n]);
	v_permlane16_swap_b32_e32 v158, v160
	v_permlane16_swap_b32_e32 v159, v161
	v_permlane16_swap_b32_e32 v194, v196
	v_permlane16_swap_b32_e32 v195, v197
	v_lshlrev_b32_e32 v136, 16, v158
	v_and_b32_e32 v137, 0xffff0000, v158
	v_lshlrev_b32_e32 v138, 16, v159
	v_and_b32_e32 v139, 0xffff0000, v159
	v_lshlrev_b32_e32 v140, 16, v160
	v_and_b32_e32 v141, 0xffff0000, v160
	v_lshlrev_b32_e32 v142, 16, v161
	v_and_b32_e32 v143, 0xffff0000, v161
	v_lshlrev_b32_e32 v144, 16, v194
	v_and_b32_e32 v145, 0xffff0000, v194
	v_lshlrev_b32_e32 v146, 16, v195
	v_and_b32_e32 v147, 0xffff0000, v195
	v_lshlrev_b32_e32 v234, 16, v196
	v_and_b32_e32 v235, 0xffff0000, v196
	v_lshlrev_b32_e32 v236, 16, v197
	v_and_b32_e32 v237, 0xffff0000, v197
	v_pk_fma_f32 v[52:53], v[52:53], v[144:145], v[136:137]
	v_pk_fma_f32 v[54:55], v[54:55], v[146:147], v[138:139]
	v_pk_fma_f32 v[48:49], v[48:49], v[234:235], v[140:141]
	v_pk_fma_f32 v[50:51], v[50:51], v[236:237], v[142:143]
	s_nop 0
	v_cvt_pk_bf16_f32 v52, v52, v53
	v_cvt_pk_bf16_f32 v53, v54, v55
	v_cvt_pk_bf16_f32 v54, v48, v49
	v_cvt_pk_bf16_f32 v55, v50, v51
	s_nop 1
	v_permlane16_swap_b32_e32 v52, v54
	v_permlane16_swap_b32_e32 v53, v55
	global_store_dwordx4 v244, v[52:55], s[90:91] offset:256
	s_waitcnt vmcnt(18)
	v_permlane16_swap_b32_e32 v162, v164
	v_permlane16_swap_b32_e32 v163, v165
	v_permlane16_swap_b32_e32 v198, v200
	v_permlane16_swap_b32_e32 v199, v201
	v_lshlrev_b32_e32 v136, 16, v162
	v_and_b32_e32 v137, 0xffff0000, v162
	v_lshlrev_b32_e32 v138, 16, v163
	v_and_b32_e32 v139, 0xffff0000, v163
	v_lshlrev_b32_e32 v140, 16, v164
	v_and_b32_e32 v141, 0xffff0000, v164
	v_lshlrev_b32_e32 v142, 16, v165
	v_and_b32_e32 v143, 0xffff0000, v165
	v_lshlrev_b32_e32 v144, 16, v198
	v_and_b32_e32 v145, 0xffff0000, v198
	v_lshlrev_b32_e32 v146, 16, v199
	v_and_b32_e32 v147, 0xffff0000, v199
	v_lshlrev_b32_e32 v234, 16, v200
	v_and_b32_e32 v235, 0xffff0000, v200
	v_lshlrev_b32_e32 v236, 16, v201
	v_and_b32_e32 v237, 0xffff0000, v201
	v_pk_fma_f32 v[44:45], v[44:45], v[144:145], v[136:137]
	v_pk_fma_f32 v[46:47], v[46:47], v[146:147], v[138:139]
	v_pk_fma_f32 v[40:41], v[40:41], v[234:235], v[140:141]
	v_pk_fma_f32 v[42:43], v[42:43], v[236:237], v[142:143]
	s_nop 0
	v_cvt_pk_bf16_f32 v44, v44, v45
	v_cvt_pk_bf16_f32 v45, v46, v47
	v_cvt_pk_bf16_f32 v46, v40, v41
	v_cvt_pk_bf16_f32 v47, v42, v43
	s_nop 1
	v_permlane16_swap_b32_e32 v44, v46
	v_permlane16_swap_b32_e32 v45, v47
	global_store_dwordx4 v245, v[44:47], s[90:91]
	s_waitcnt vmcnt(16)
	v_permlane16_swap_b32_e32 v166, v168
	v_permlane16_swap_b32_e32 v167, v169
	v_permlane16_swap_b32_e32 v202, v204
	v_permlane16_swap_b32_e32 v203, v205
	v_lshlrev_b32_e32 v136, 16, v166
	v_and_b32_e32 v137, 0xffff0000, v166
	v_lshlrev_b32_e32 v138, 16, v167
	v_and_b32_e32 v139, 0xffff0000, v167
	v_lshlrev_b32_e32 v140, 16, v168
	v_and_b32_e32 v141, 0xffff0000, v168
	v_lshlrev_b32_e32 v142, 16, v169
	v_and_b32_e32 v143, 0xffff0000, v169
	v_lshlrev_b32_e32 v144, 16, v202
	v_and_b32_e32 v145, 0xffff0000, v202
	v_lshlrev_b32_e32 v146, 16, v203
	v_and_b32_e32 v147, 0xffff0000, v203
	v_lshlrev_b32_e32 v234, 16, v204
	v_and_b32_e32 v235, 0xffff0000, v204
	v_lshlrev_b32_e32 v236, 16, v205
	v_and_b32_e32 v237, 0xffff0000, v205
	v_pk_fma_f32 v[36:37], v[36:37], v[144:145], v[136:137]
	v_pk_fma_f32 v[38:39], v[38:39], v[146:147], v[138:139]
	v_pk_fma_f32 v[32:33], v[32:33], v[234:235], v[140:141]
	v_pk_fma_f32 v[34:35], v[34:35], v[236:237], v[142:143]
	s_nop 0
	v_cvt_pk_bf16_f32 v36, v36, v37
	v_cvt_pk_bf16_f32 v37, v38, v39
	v_cvt_pk_bf16_f32 v38, v32, v33
	v_cvt_pk_bf16_f32 v39, v34, v35
	s_nop 1
	v_permlane16_swap_b32_e32 v36, v38
	v_permlane16_swap_b32_e32 v37, v39
	global_store_dwordx4 v245, v[36:39], s[90:91] offset:256
	s_waitcnt vmcnt(14)
	v_permlane16_swap_b32_e32 v170, v172
	v_permlane16_swap_b32_e32 v171, v173
	v_permlane16_swap_b32_e32 v206, v208
	v_permlane16_swap_b32_e32 v207, v209
	v_lshlrev_b32_e32 v136, 16, v170
	v_and_b32_e32 v137, 0xffff0000, v170
	v_lshlrev_b32_e32 v138, 16, v171
	v_and_b32_e32 v139, 0xffff0000, v171
	v_lshlrev_b32_e32 v140, 16, v172
	v_and_b32_e32 v141, 0xffff0000, v172
	v_lshlrev_b32_e32 v142, 16, v173
	v_and_b32_e32 v143, 0xffff0000, v173
	v_lshlrev_b32_e32 v144, 16, v206
	v_and_b32_e32 v145, 0xffff0000, v206
	v_lshlrev_b32_e32 v146, 16, v207
	v_and_b32_e32 v147, 0xffff0000, v207
	v_lshlrev_b32_e32 v234, 16, v208
	v_and_b32_e32 v235, 0xffff0000, v208
	v_lshlrev_b32_e32 v236, 16, v209
	v_and_b32_e32 v237, 0xffff0000, v209
	v_pk_fma_f32 v[28:29], v[28:29], v[144:145], v[136:137]
	v_pk_fma_f32 v[30:31], v[30:31], v[146:147], v[138:139]
	v_pk_fma_f32 v[24:25], v[24:25], v[234:235], v[140:141]
	v_pk_fma_f32 v[26:27], v[26:27], v[236:237], v[142:143]
	s_nop 0
	v_cvt_pk_bf16_f32 v28, v28, v29
	v_cvt_pk_bf16_f32 v29, v30, v31
	v_cvt_pk_bf16_f32 v30, v24, v25
	v_cvt_pk_bf16_f32 v31, v26, v27
	s_nop 1
	v_permlane16_swap_b32_e32 v28, v30
	v_permlane16_swap_b32_e32 v29, v31
	global_store_dwordx4 v246, v[28:31], s[90:91]
	s_waitcnt vmcnt(12)
; #define PG8_BAR __builtin_amdgcn_s_barrier()
; template <class Epi, class Sched, bool DEFER>
; __device__ __forceinline__ void gemm_fast_core(LAS unsigned char* lds, const GemmP g, const Sched& S, const Epi& E, f32x4 (&acc)[2][2][4][2], Unit& cur) {
;     ...
;             const int row0 = cur.pm * BM + wr * 64 + fr, col0 = cur.pn * BM + wc * 32 + 4 * fq;
; #pragma unroll
;             for (int ai = 0; ai < 2; ++ai)
; #pragma unroll
;                 for (int m = 0; m < 4; ++m)
; #pragma unroll
;                     for (int bj = 0; bj < 2; ++bj)
; #pragma unroll
;                         for (int n = 0; n < 2; ++n) E.put(cur, row0 + ai * HALF + m * 16, col0 + bj * HALF + n * 16, acc[ai][bj][m][n]);
;     ...
;         if (!has_next) break;
; #pragma unroll
;         for (int a = 0; a < 2; ++a)
; #pragma unroll
;             for (int b = 0; b < 2; ++b)
; #pragma unroll
;                 for (int m = 0; m < 4; ++m)
; #pragma unroll
;                     for (int n = 0; n < 2; ++n) acc[a][b][m][n] = (f32x4){0.f, 0.f, 0.f, 0.f};
;         cur = nxt; cA = nA; cB = nB; ++ui;
;         if (wr == 1) PG8_BAR;
	v_permlane16_swap_b32_e32 v174, v176
	v_permlane16_swap_b32_e32 v175, v177
	v_permlane16_swap_b32_e32 v210, v212
	v_permlane16_swap_b32_e32 v211, v213
	v_lshlrev_b32_e32 v136, 16, v174
	v_and_b32_e32 v137, 0xffff0000, v174
	v_lshlrev_b32_e32 v138, 16, v175
	v_and_b32_e32 v139, 0xffff0000, v175
	v_lshlrev_b32_e32 v140, 16, v176
	v_and_b32_e32 v141, 0xffff0000, v176
	v_lshlrev_b32_e32 v142, 16, v177
	v_and_b32_e32 v143, 0xffff0000, v177
	v_lshlrev_b32_e32 v144, 16, v210
	v_and_b32_e32 v145, 0xffff0000, v210
	v_lshlrev_b32_e32 v146, 16, v211
	v_and_b32_e32 v147, 0xffff0000, v211
	v_lshlrev_b32_e32 v234, 16, v212
	v_and_b32_e32 v235, 0xffff0000, v212
	v_lshlrev_b32_e32 v236, 16, v213
	v_and_b32_e32 v237, 0xffff0000, v213
	v_pk_fma_f32 v[20:21], v[20:21], v[144:145], v[136:137]
	v_pk_fma_f32 v[22:23], v[22:23], v[146:147], v[138:139]
	v_pk_fma_f32 v[16:17], v[16:17], v[234:235], v[140:141]
	v_pk_fma_f32 v[18:19], v[18:19], v[236:237], v[142:143]
	s_nop 0
	v_cvt_pk_bf16_f32 v20, v20, v21
	v_cvt_pk_bf16_f32 v21, v22, v23
	v_cvt_pk_bf16_f32 v22, v16, v17
	v_cvt_pk_bf16_f32 v23, v18, v19
	s_nop 1
	v_permlane16_swap_b32_e32 v20, v22
	v_permlane16_swap_b32_e32 v21, v23
	global_store_dwordx4 v246, v[20:23], s[90:91] offset:256
	s_waitcnt vmcnt(10)
	v_permlane16_swap_b32_e32 v178, v180
	v_permlane16_swap_b32_e32 v179, v181
	v_permlane16_swap_b32_e32 v214, v216
	v_permlane16_swap_b32_e32 v215, v217
	v_lshlrev_b32_e32 v136, 16, v178
	v_and_b32_e32 v137, 0xffff0000, v178
	v_lshlrev_b32_e32 v138, 16, v179
	v_and_b32_e32 v139, 0xffff0000, v179
	v_lshlrev_b32_e32 v140, 16, v180
	v_and_b32_e32 v141, 0xffff0000, v180
	v_lshlrev_b32_e32 v142, 16, v181
	v_and_b32_e32 v143, 0xffff0000, v181
	v_lshlrev_b32_e32 v144, 16, v214
	v_and_b32_e32 v145, 0xffff0000, v214
	v_lshlrev_b32_e32 v146, 16, v215
	v_and_b32_e32 v147, 0xffff0000, v215
	v_lshlrev_b32_e32 v234, 16, v216
	v_and_b32_e32 v235, 0xffff0000, v216
	v_lshlrev_b32_e32 v236, 16, v217
	v_and_b32_e32 v237, 0xffff0000, v217
	v_pk_fma_f32 v[12:13], v[12:13], v[144:145], v[136:137]
	v_pk_fma_f32 v[14:15], v[14:15], v[146:147], v[138:139]
	v_pk_fma_f32 v[8:9], v[8:9], v[234:235], v[140:141]
	v_pk_fma_f32 v[10:11], v[10:11], v[236:237], v[142:143]
	s_nop 0
	v_cvt_pk_bf16_f32 v12, v12, v13
	v_cvt_pk_bf16_f32 v13, v14, v15
	v_cvt_pk_bf16_f32 v14, v8, v9
	v_cvt_pk_bf16_f32 v15, v10, v11
	s_nop 1
	v_permlane16_swap_b32_e32 v12, v14
	v_permlane16_swap_b32_e32 v13, v15
	global_store_dwordx4 v247, v[12:15], s[90:91]
	s_waitcnt vmcnt(8)
	v_permlane16_swap_b32_e32 v182, v184
	v_permlane16_swap_b32_e32 v183, v185
	v_permlane16_swap_b32_e32 v230, v232
	v_permlane16_swap_b32_e32 v231, v233
	v_lshlrev_b32_e32 v136, 16, v182
	v_and_b32_e32 v137, 0xffff0000, v182
	v_lshlrev_b32_e32 v138, 16, v183
	v_and_b32_e32 v139, 0xffff0000, v183
	v_lshlrev_b32_e32 v140, 16, v184
	v_and_b32_e32 v141, 0xffff0000, v184
	v_lshlrev_b32_e32 v142, 16, v185
	v_and_b32_e32 v143, 0xffff0000, v185
	v_lshlrev_b32_e32 v144, 16, v230
	v_and_b32_e32 v145, 0xffff0000, v230
	v_lshlrev_b32_e32 v146, 16, v231
	v_and_b32_e32 v147, 0xffff0000, v231
	v_lshlrev_b32_e32 v234, 16, v232
	v_and_b32_e32 v235, 0xffff0000, v232
	v_lshlrev_b32_e32 v236, 16, v233
	v_and_b32_e32 v237, 0xffff0000, v233
	v_pk_fma_f32 v[4:5], v[4:5], v[144:145], v[136:137]
	v_pk_fma_f32 v[6:7], v[6:7], v[146:147], v[138:139]
	v_pk_fma_f32 v[0:1], v[0:1], v[234:235], v[140:141]
	v_pk_fma_f32 v[2:3], v[2:3], v[236:237], v[142:143]
	s_nop 0
	v_cvt_pk_bf16_f32 v4, v4, v5
	v_cvt_pk_bf16_f32 v5, v6, v7
	v_cvt_pk_bf16_f32 v6, v0, v1
	v_cvt_pk_bf16_f32 v7, v2, v3
	s_nop 1
	v_permlane16_swap_b32_e32 v4, v6
	v_permlane16_swap_b32_e32 v5, v7
	global_store_dwordx4 v247, v[4:7], s[90:91] offset:256
.Lp6e_done:
	s_mov_b64 s[4:5], -1
	s_and_b64 vcc, exec, s[20:21]
	s_cbranch_vccz .LBB0_1408
.LBB0_1542:
	s_and_b64 vcc, exec, s[2:3]
	s_cbranch_vccz .LBB0_1407
	s_barrier
	s_branch .LBB0_1407

; __device__ __forceinline__ void st_bf4(bf16_t* p, f32x4 v) { u32x2 w; w.x = pk2(v[0], v[1]); w.y = pk2(v[2], v[3]); *(u32x2*)p = w; }
; __device__ __forceinline__ float row_rstd(const float* slots, int row) {
;     const unsigned long long* sp = (const unsigned long long*)(slots + (size_t)row * 8); float t = 0.f;
; #pragma unroll
;     for (int q = 0; q < 4; ++q) { const unsigned long long w = __hip_atomic_load(sp + q, __ATOMIC_RELAXED, __HIP_MEMORY_SCOPE_AGENT); t += __uint_as_float((unsigned)w) + __uint_as_float((unsigned)(w >> 32)); }
;     return rsqrtf(t * (1.0f / DM) + EPS);
; }
; __global__ void __launch_bounds__(NTHR, 2) fwd_kernel(Args a) {
;     ...
;         int tid2 = threadIdx.x; asm volatile("" : "+v"(tid2));
;         { const int wid2 = __builtin_amdgcn_readfirstlane(tid2 >> 6), colg = u.pn * BM + 4 * (tid2 & 63); const float* md = mod + ((u.pm * BM) >> 11) * MODW;
;           const f32x4 gg = *(const f32x4*)(a.in[I_G2] + colg), sh = *(const f32x4*)(md + 3 * DM + colg), sc = *(const f32x4*)(md + 4 * DM + colg) + 1.0f;
; #pragma unroll
;           for (int ai = 0; ai < 2; ++ai)
; #pragma unroll
;               for (int j = 0; j < 16; ++j) { const int row = u.pm * BM + ai * HALF + wid2 * 16 + j; const float rstd = row_rstd(slots1, row);
;                   st_bf4(H2 + (size_t)row * DM + colg, (xr[ai][j] * rstd * gg) * sc + sh); }
;         }
.LBB0_1738:
	s_or_b64 exec, exec, s[2:3]
	s_waitcnt lgkmcnt(0)
	v_mov_b32_e32 v0, v189
	s_barrier
	v_readfirstlane_b32 s2, v0
	v_lshlrev_b32_e32 v0, 2, v0
	v_and_b32_e32 v0, 0xfc, v0
	v_or_b32_e32 v136, s48, v0
	v_ashrrev_i32_e32 v137, 31, v136
	v_lshlrev_b64 v[4:5], 2, v[136:137]
	v_lshl_add_u64 v[0:1], s[52:53], 0, v[4:5]
	v_lshl_add_u64 v[4:5], s[0:1], 0, v[4:5]
	s_movk_i32 s0, 0x6000
	v_add_co_u32_e32 v6, vcc, s0, v4
	s_mov_b32 s0, 0x8000
	s_nop 0
	v_addc_co_u32_e32 v7, vcc, 0, v5, vcc
	v_add_co_u32_e32 v138, vcc, s0, v4
	s_ashr_i32 s0, s2, 2
	s_and_b32 s0, s0, -16
	s_add_i32 s0, s0, s49
	v_addc_co_u32_e32 v139, vcc, 0, v5, vcc
	global_load_dwordx4 v[0:3], v[0:1], off
	global_load_dwordx4 v[4:7], v[6:7], off
	global_load_dwordx4 v[144:147], v[138:139], off
	v_lshl_add_u64 v[136:137], v[136:137], 1, s[90:91]
	v_and_b32_e32 v142, 31, v189
	v_and_b32_e32 v153, 15, v142
	v_lshrrev_b32_e32 v142, 4, v142
	v_lshl_add_u32 v153, v142, 7, v153
	v_add_u32_e32 v153, s0, v153
	v_lshlrev_b32_e32 v143, 5, v153
	global_load_dwordx4 v[148:151], v143, s[46:47] sc1
	global_load_dwordx4 v[138:141], v143, s[46:47] offset:16 sc1
	v_mov_b32_e32 v152, 0x358637bd
	s_mov_b32 s2, 0x800000
	s_waitcnt vmcnt(0)
	v_add_f32_e32 v148, v148, v149
	v_add_f32_e32 v149, v150, v151
	v_add_f32_e32 v148, 0, v148
	v_add_f32_e32 v150, v138, v139
	v_add_f32_e32 v148, v148, v149
	v_add_f32_e32 v151, v140, v141
	v_add_f32_e32 v148, v148, v150
	v_add_f32_e32 v148, v148, v151
	v_fmamk_f32 v148, v148, 0x3a000000, v152
	v_mul_f32_e32 v149, 0x4b800000, v148
	v_cmp_gt_f32_e32 vcc, s2, v148
	s_nop 1
	v_cndmask_b32_e32 v148, v148, v149, vcc
	v_rsq_f32_e32 v148, v148
	s_nop 0
	v_mul_f32_e32 v149, 0x45800000, v148
	v_cndmask_b32_e32 v143, v148, v149, vcc
	v_pk_add_f32 v[140:141], v[144:145], 1.0 op_sel_hi:[1,0]
	v_pk_add_f32 v[138:139], v[146:147], 1.0 op_sel_hi:[1,0]
	s_mov_b32 s7, 0
	v_readlane_b32 s4, v143, 0
	s_add_i32 s6, s0, 0
	s_lshl_b32 s6, s6, 12
	v_lshl_add_u64 v[148:149], v[136:137], 0, s[6:7]
	v_pk_mul_f32 v[68:69], v[68:69], s[4:5] op_sel_hi:[1,0]
	v_pk_mul_f32 v[70:71], v[70:71], s[4:5] op_sel_hi:[1,0]
	v_pk_mul_f32 v[68:69], v[2:3], v[68:69]
	v_pk_mul_f32 v[70:71], v[0:1], v[70:71]
	v_pk_fma_f32 v[68:69], v[138:139], v[68:69], v[6:7]
	v_pk_fma_f32 v[70:71], v[140:141], v[70:71], v[4:5]
	s_nop 0
	v_cvt_pk_bf16_f32 v70, v70, v71
	v_cvt_pk_bf16_f32 v71, v68, v69
	global_store_dwordx2 v[148:149], v[70:71], off
	v_readlane_b32 s4, v143, 1
	s_add_i32 s6, s0, 1
	s_lshl_b32 s6, s6, 12
	v_lshl_add_u64 v[150:151], v[136:137], 0, s[6:7]
	v_pk_mul_f32 v[72:73], v[72:73], s[4:5] op_sel_hi:[1,0]
	v_pk_mul_f32 v[74:75], v[74:75], s[4:5] op_sel_hi:[1,0]
	v_pk_mul_f32 v[72:73], v[2:3], v[72:73]
	v_pk_mul_f32 v[74:75], v[0:1], v[74:75]
	v_pk_fma_f32 v[72:73], v[138:139], v[72:73], v[6:7]
	v_pk_fma_f32 v[74:75], v[140:141], v[74:75], v[4:5]
	s_nop 0
	v_cvt_pk_bf16_f32 v74, v74, v75
	v_cvt_pk_bf16_f32 v75, v72, v73
	global_store_dwordx2 v[150:151], v[74:75], off
	v_readlane_b32 s4, v143, 2
	s_add_i32 s6, s0, 2
	s_lshl_b32 s6, s6, 12
	v_lshl_add_u64 v[148:149], v[136:137], 0, s[6:7]
	v_pk_mul_f32 v[76:77], v[76:77], s[4:5] op_sel_hi:[1,0]
	v_pk_mul_f32 v[78:79], v[78:79], s[4:5] op_sel_hi:[1,0]
	v_pk_mul_f32 v[76:77], v[2:3], v[76:77]
	v_pk_mul_f32 v[78:79], v[0:1], v[78:79]
	v_pk_fma_f32 v[76:77], v[138:139], v[76:77], v[6:7]
	v_pk_fma_f32 v[78:79], v[140:141], v[78:79], v[4:5]
	s_nop 0
	v_cvt_pk_bf16_f32 v78, v78, v79
	v_cvt_pk_bf16_f32 v79, v76, v77
	global_store_dwordx2 v[148:149], v[78:79], off
	v_readlane_b32 s4, v143, 3
	s_add_i32 s6, s0, 3
	s_lshl_b32 s6, s6, 12
	v_lshl_add_u64 v[150:151], v[136:137], 0, s[6:7]
	v_pk_mul_f32 v[80:81], v[80:81], s[4:5] op_sel_hi:[1,0]
	v_pk_mul_f32 v[82:83], v[82:83], s[4:5] op_sel_hi:[1,0]
	v_pk_mul_f32 v[80:81], v[2:3], v[80:81]
	v_pk_mul_f32 v[82:83], v[0:1], v[82:83]
	v_pk_fma_f32 v[80:81], v[138:139], v[80:81], v[6:7]
	v_pk_fma_f32 v[82:83], v[140:141], v[82:83], v[4:5]
	s_nop 0
	v_cvt_pk_bf16_f32 v82, v82, v83
	v_cvt_pk_bf16_f32 v83, v80, v81
	global_store_dwordx2 v[150:151], v[82:83], off
	v_readlane_b32 s4, v143, 4
	s_add_i32 s6, s0, 4
	s_lshl_b32 s6, s6, 12
	v_lshl_add_u64 v[148:149], v[136:137], 0, s[6:7]
	v_pk_mul_f32 v[84:85], v[84:85], s[4:5] op_sel_hi:[1,0]
	v_pk_mul_f32 v[86:87], v[86:87], s[4:5] op_sel_hi:[1,0]
	v_pk_mul_f32 v[84:85], v[2:3], v[84:85]
	v_pk_mul_f32 v[86:87], v[0:1], v[86:87]
	v_pk_fma_f32 v[84:85], v[138:139], v[84:85], v[6:7]
	v_pk_fma_f32 v[86:87], v[140:141], v[86:87], v[4:5]
	s_nop 0
	v_cvt_pk_bf16_f32 v86, v86, v87
	v_cvt_pk_bf16_f32 v87, v84, v85
	global_store_dwordx2 v[148:149], v[86:87], off
	v_readlane_b32 s4, v143, 5
	s_add_i32 s6, s0, 5
	s_lshl_b32 s6, s6, 12
	v_lshl_add_u64 v[150:151], v[136:137], 0, s[6:7]
	v_pk_mul_f32 v[88:89], v[88:89], s[4:5] op_sel_hi:[1,0]
	v_pk_mul_f32 v[90:91], v[90:91], s[4:5] op_sel_hi:[1,0]
	v_pk_mul_f32 v[88:89], v[2:3], v[88:89]
	v_pk_mul_f32 v[90:91], v[0:1], v[90:91]
	v_pk_fma_f32 v[88:89], v[138:139], v[88:89], v[6:7]
	v_pk_fma_f32 v[90:91], v[140:141], v[90:91], v[4:5]
	s_nop 0
	v_cvt_pk_bf16_f32 v90, v90, v91
	v_cvt_pk_bf16_f32 v91, v88, v89
	global_store_dwordx2 v[150:151], v[90:91], off
	v_readlane_b32 s4, v143, 6
	s_add_i32 s6, s0, 6
	s_lshl_b32 s6, s6, 12
	v_lshl_add_u64 v[148:149], v[136:137], 0, s[6:7]
	v_pk_mul_f32 v[92:93], v[92:93], s[4:5] op_sel_hi:[1,0]
	v_pk_mul_f32 v[94:95], v[94:95], s[4:5] op_sel_hi:[1,0]
	v_pk_mul_f32 v[92:93], v[2:3], v[92:93]
	v_pk_mul_f32 v[94:95], v[0:1], v[94:95]
	v_pk_fma_f32 v[92:93], v[138:139], v[92:93], v[6:7]
	v_pk_fma_f32 v[94:95], v[140:141], v[94:95], v[4:5]
	s_nop 0
	v_cvt_pk_bf16_f32 v94, v94, v95
	v_cvt_pk_bf16_f32 v95, v92, v93
; __device__ __forceinline__ void st_bf4(bf16_t* p, f32x4 v) { u32x2 w; w.x = pk2(v[0], v[1]); w.y = pk2(v[2], v[3]); *(u32x2*)p = w; }
; __global__ void __launch_bounds__(NTHR, 2) fwd_kernel(Args a) {
;     ...
;           for (int ai = 0; ai < 2; ++ai)
; #pragma unroll
;               for (int j = 0; j < 16; ++j) { const int row = u.pm * BM + ai * HALF + wid2 * 16 + j; const float rstd = row_rstd(slots1, row);
;                   st_bf4(H2 + (size_t)row * DM + colg, (xr[ai][j] * rstd * gg) * sc + sh); }
;         }
	global_store_dwordx2 v[148:149], v[94:95], off
	v_readlane_b32 s4, v143, 7
	s_add_i32 s6, s0, 7
	s_lshl_b32 s6, s6, 12
	v_lshl_add_u64 v[150:151], v[136:137], 0, s[6:7]
	v_pk_mul_f32 v[96:97], v[96:97], s[4:5] op_sel_hi:[1,0]
	v_pk_mul_f32 v[98:99], v[98:99], s[4:5] op_sel_hi:[1,0]
	v_pk_mul_f32 v[96:97], v[2:3], v[96:97]
	v_pk_mul_f32 v[98:99], v[0:1], v[98:99]
	v_pk_fma_f32 v[96:97], v[138:139], v[96:97], v[6:7]
	v_pk_fma_f32 v[98:99], v[140:141], v[98:99], v[4:5]
	s_nop 0
	v_cvt_pk_bf16_f32 v98, v98, v99
	v_cvt_pk_bf16_f32 v99, v96, v97
	global_store_dwordx2 v[150:151], v[98:99], off
	v_readlane_b32 s4, v143, 8
	s_add_i32 s6, s0, 8
	s_lshl_b32 s6, s6, 12
	v_lshl_add_u64 v[148:149], v[136:137], 0, s[6:7]
	v_pk_mul_f32 v[100:101], v[100:101], s[4:5] op_sel_hi:[1,0]
	v_pk_mul_f32 v[102:103], v[102:103], s[4:5] op_sel_hi:[1,0]
	v_pk_mul_f32 v[100:101], v[2:3], v[100:101]
	v_pk_mul_f32 v[102:103], v[0:1], v[102:103]
	v_pk_fma_f32 v[100:101], v[138:139], v[100:101], v[6:7]
	v_pk_fma_f32 v[102:103], v[140:141], v[102:103], v[4:5]
	s_nop 0
	v_cvt_pk_bf16_f32 v102, v102, v103
	v_cvt_pk_bf16_f32 v103, v100, v101
	global_store_dwordx2 v[148:149], v[102:103], off
	v_readlane_b32 s4, v143, 9
	s_add_i32 s6, s0, 9
	s_lshl_b32 s6, s6, 12
	v_lshl_add_u64 v[150:151], v[136:137], 0, s[6:7]
	v_pk_mul_f32 v[104:105], v[104:105], s[4:5] op_sel_hi:[1,0]
	v_pk_mul_f32 v[106:107], v[106:107], s[4:5] op_sel_hi:[1,0]
	v_pk_mul_f32 v[104:105], v[2:3], v[104:105]
	v_pk_mul_f32 v[106:107], v[0:1], v[106:107]
	v_pk_fma_f32 v[104:105], v[138:139], v[104:105], v[6:7]
	v_pk_fma_f32 v[106:107], v[140:141], v[106:107], v[4:5]
	s_nop 0
	v_cvt_pk_bf16_f32 v106, v106, v107
	v_cvt_pk_bf16_f32 v107, v104, v105
	global_store_dwordx2 v[150:151], v[106:107], off
	v_readlane_b32 s4, v143, 10
	s_add_i32 s6, s0, 10
	s_lshl_b32 s6, s6, 12
	v_lshl_add_u64 v[148:149], v[136:137], 0, s[6:7]
	v_pk_mul_f32 v[108:109], v[108:109], s[4:5] op_sel_hi:[1,0]
	v_pk_mul_f32 v[110:111], v[110:111], s[4:5] op_sel_hi:[1,0]
	v_pk_mul_f32 v[108:109], v[2:3], v[108:109]
	v_pk_mul_f32 v[110:111], v[0:1], v[110:111]
	v_pk_fma_f32 v[108:109], v[138:139], v[108:109], v[6:7]
	v_pk_fma_f32 v[110:111], v[140:141], v[110:111], v[4:5]
	s_nop 0
	v_cvt_pk_bf16_f32 v110, v110, v111
	v_cvt_pk_bf16_f32 v111, v108, v109
	global_store_dwordx2 v[148:149], v[110:111], off
	v_readlane_b32 s4, v143, 11
	s_add_i32 s6, s0, 11
	s_lshl_b32 s6, s6, 12
	v_lshl_add_u64 v[150:151], v[136:137], 0, s[6:7]
	v_pk_mul_f32 v[112:113], v[112:113], s[4:5] op_sel_hi:[1,0]
	v_pk_mul_f32 v[114:115], v[114:115], s[4:5] op_sel_hi:[1,0]
	v_pk_mul_f32 v[112:113], v[2:3], v[112:113]
	v_pk_mul_f32 v[114:115], v[0:1], v[114:115]
	v_pk_fma_f32 v[112:113], v[138:139], v[112:113], v[6:7]
	v_pk_fma_f32 v[114:115], v[140:141], v[114:115], v[4:5]
	s_nop 0
	v_cvt_pk_bf16_f32 v114, v114, v115
	v_cvt_pk_bf16_f32 v115, v112, v113
	global_store_dwordx2 v[150:151], v[114:115], off
	v_readlane_b32 s4, v143, 12
	s_add_i32 s6, s0, 12
	s_lshl_b32 s6, s6, 12
	v_lshl_add_u64 v[148:149], v[136:137], 0, s[6:7]
	v_pk_mul_f32 v[116:117], v[116:117], s[4:5] op_sel_hi:[1,0]
	v_pk_mul_f32 v[118:119], v[118:119], s[4:5] op_sel_hi:[1,0]
	v_pk_mul_f32 v[116:117], v[2:3], v[116:117]
	v_pk_mul_f32 v[118:119], v[0:1], v[118:119]
	v_pk_fma_f32 v[116:117], v[138:139], v[116:117], v[6:7]
	v_pk_fma_f32 v[118:119], v[140:141], v[118:119], v[4:5]
	s_nop 0
	v_cvt_pk_bf16_f32 v118, v118, v119
	v_cvt_pk_bf16_f32 v119, v116, v117
	global_store_dwordx2 v[148:149], v[118:119], off
	v_readlane_b32 s4, v143, 13
	s_add_i32 s6, s0, 13
	s_lshl_b32 s6, s6, 12
	v_lshl_add_u64 v[150:151], v[136:137], 0, s[6:7]
	v_pk_mul_f32 v[120:121], v[120:121], s[4:5] op_sel_hi:[1,0]
	v_pk_mul_f32 v[122:123], v[122:123], s[4:5] op_sel_hi:[1,0]
	v_pk_mul_f32 v[120:121], v[2:3], v[120:121]
	v_pk_mul_f32 v[122:123], v[0:1], v[122:123]
	v_pk_fma_f32 v[120:121], v[138:139], v[120:121], v[6:7]
	v_pk_fma_f32 v[122:123], v[140:141], v[122:123], v[4:5]
	s_nop 0
	v_cvt_pk_bf16_f32 v122, v122, v123
	v_cvt_pk_bf16_f32 v123, v120, v121
	global_store_dwordx2 v[150:151], v[122:123], off
	v_readlane_b32 s4, v143, 14
	s_add_i32 s6, s0, 14
	s_lshl_b32 s6, s6, 12
	v_lshl_add_u64 v[148:149], v[136:137], 0, s[6:7]
	v_pk_mul_f32 v[124:125], v[124:125], s[4:5] op_sel_hi:[1,0]
	v_pk_mul_f32 v[126:127], v[126:127], s[4:5] op_sel_hi:[1,0]
	v_pk_mul_f32 v[124:125], v[2:3], v[124:125]
	v_pk_mul_f32 v[126:127], v[0:1], v[126:127]
	v_pk_fma_f32 v[124:125], v[138:139], v[124:125], v[6:7]
	v_pk_fma_f32 v[126:127], v[140:141], v[126:127], v[4:5]
	s_nop 0
	v_cvt_pk_bf16_f32 v126, v126, v127
	v_cvt_pk_bf16_f32 v127, v124, v125
	global_store_dwordx2 v[148:149], v[126:127], off
	v_readlane_b32 s4, v143, 15
	s_add_i32 s6, s0, 15
	s_lshl_b32 s6, s6, 12
	v_lshl_add_u64 v[150:151], v[136:137], 0, s[6:7]
	v_pk_mul_f32 v[128:129], v[128:129], s[4:5] op_sel_hi:[1,0]
	v_pk_mul_f32 v[130:131], v[130:131], s[4:5] op_sel_hi:[1,0]
	v_pk_mul_f32 v[128:129], v[2:3], v[128:129]
	v_pk_mul_f32 v[130:131], v[0:1], v[130:131]
	v_pk_fma_f32 v[128:129], v[138:139], v[128:129], v[6:7]
	v_pk_fma_f32 v[130:131], v[140:141], v[130:131], v[4:5]
	s_nop 0
	v_cvt_pk_bf16_f32 v130, v130, v131
	v_cvt_pk_bf16_f32 v131, v128, v129
	global_store_dwordx2 v[150:151], v[130:131], off
	v_readlane_b32 s4, v143, 16
	s_add_i32 s6, s0, 128
	s_lshl_b32 s6, s6, 12
	v_lshl_add_u64 v[148:149], v[136:137], 0, s[6:7]
	v_pk_mul_f32 v[8:9], v[8:9], s[4:5] op_sel_hi:[1,0]
	v_pk_mul_f32 v[10:11], v[10:11], s[4:5] op_sel_hi:[1,0]
	v_pk_mul_f32 v[8:9], v[2:3], v[8:9]
	v_pk_mul_f32 v[10:11], v[0:1], v[10:11]
	v_pk_fma_f32 v[8:9], v[138:139], v[8:9], v[6:7]
	v_pk_fma_f32 v[10:11], v[140:141], v[10:11], v[4:5]
; __device__ __forceinline__ void st_bf4(bf16_t* p, f32x4 v) { u32x2 w; w.x = pk2(v[0], v[1]); w.y = pk2(v[2], v[3]); *(u32x2*)p = w; }
; __global__ void __launch_bounds__(NTHR, 2) fwd_kernel(Args a) {
;     ...
;           for (int ai = 0; ai < 2; ++ai)
; #pragma unroll
;               for (int j = 0; j < 16; ++j) { const int row = u.pm * BM + ai * HALF + wid2 * 16 + j; const float rstd = row_rstd(slots1, row);
;                   st_bf4(H2 + (size_t)row * DM + colg, (xr[ai][j] * rstd * gg) * sc + sh); }
;         }
	s_nop 0
	v_cvt_pk_bf16_f32 v10, v10, v11
	v_cvt_pk_bf16_f32 v11, v8, v9
	global_store_dwordx2 v[148:149], v[10:11], off
	v_readlane_b32 s4, v143, 17
	s_add_i32 s6, s0, 129
	s_lshl_b32 s6, s6, 12
	v_lshl_add_u64 v[150:151], v[136:137], 0, s[6:7]
	v_pk_mul_f32 v[12:13], v[12:13], s[4:5] op_sel_hi:[1,0]
	v_pk_mul_f32 v[14:15], v[14:15], s[4:5] op_sel_hi:[1,0]
	v_pk_mul_f32 v[12:13], v[2:3], v[12:13]
	v_pk_mul_f32 v[14:15], v[0:1], v[14:15]
	v_pk_fma_f32 v[12:13], v[138:139], v[12:13], v[6:7]
	v_pk_fma_f32 v[14:15], v[140:141], v[14:15], v[4:5]
	s_nop 0
	v_cvt_pk_bf16_f32 v14, v14, v15
	v_cvt_pk_bf16_f32 v15, v12, v13
	global_store_dwordx2 v[150:151], v[14:15], off
	v_readlane_b32 s4, v143, 18
	s_add_i32 s6, s0, 130
	s_lshl_b32 s6, s6, 12
	v_lshl_add_u64 v[148:149], v[136:137], 0, s[6:7]
	v_pk_mul_f32 v[16:17], v[16:17], s[4:5] op_sel_hi:[1,0]
	v_pk_mul_f32 v[18:19], v[18:19], s[4:5] op_sel_hi:[1,0]
	v_pk_mul_f32 v[16:17], v[2:3], v[16:17]
	v_pk_mul_f32 v[18:19], v[0:1], v[18:19]
	v_pk_fma_f32 v[16:17], v[138:139], v[16:17], v[6:7]
	v_pk_fma_f32 v[18:19], v[140:141], v[18:19], v[4:5]
	s_nop 0
	v_cvt_pk_bf16_f32 v18, v18, v19
	v_cvt_pk_bf16_f32 v19, v16, v17
	global_store_dwordx2 v[148:149], v[18:19], off
	v_readlane_b32 s4, v143, 19
	s_add_i32 s6, s0, 131
	s_lshl_b32 s6, s6, 12
	v_lshl_add_u64 v[150:151], v[136:137], 0, s[6:7]
	v_pk_mul_f32 v[20:21], v[20:21], s[4:5] op_sel_hi:[1,0]
	v_pk_mul_f32 v[22:23], v[22:23], s[4:5] op_sel_hi:[1,0]
	v_pk_mul_f32 v[20:21], v[2:3], v[20:21]
	v_pk_mul_f32 v[22:23], v[0:1], v[22:23]
	v_pk_fma_f32 v[20:21], v[138:139], v[20:21], v[6:7]
	v_pk_fma_f32 v[22:23], v[140:141], v[22:23], v[4:5]
	s_nop 0
	v_cvt_pk_bf16_f32 v22, v22, v23
	v_cvt_pk_bf16_f32 v23, v20, v21
	global_store_dwordx2 v[150:151], v[22:23], off
	v_readlane_b32 s4, v143, 20
	s_add_i32 s6, s0, 132
	s_lshl_b32 s6, s6, 12
	v_lshl_add_u64 v[148:149], v[136:137], 0, s[6:7]
	v_pk_mul_f32 v[24:25], v[24:25], s[4:5] op_sel_hi:[1,0]
	v_pk_mul_f32 v[26:27], v[26:27], s[4:5] op_sel_hi:[1,0]
	v_pk_mul_f32 v[24:25], v[2:3], v[24:25]
	v_pk_mul_f32 v[26:27], v[0:1], v[26:27]
	v_pk_fma_f32 v[24:25], v[138:139], v[24:25], v[6:7]
	v_pk_fma_f32 v[26:27], v[140:141], v[26:27], v[4:5]
	s_nop 0
	v_cvt_pk_bf16_f32 v26, v26, v27
	v_cvt_pk_bf16_f32 v27, v24, v25
	global_store_dwordx2 v[148:149], v[26:27], off
	v_readlane_b32 s4, v143, 21
	s_add_i32 s6, s0, 133
	s_lshl_b32 s6, s6, 12
	v_lshl_add_u64 v[150:151], v[136:137], 0, s[6:7]
	v_pk_mul_f32 v[28:29], v[28:29], s[4:5] op_sel_hi:[1,0]
	v_pk_mul_f32 v[30:31], v[30:31], s[4:5] op_sel_hi:[1,0]
	v_pk_mul_f32 v[28:29], v[2:3], v[28:29]
	v_pk_mul_f32 v[30:31], v[0:1], v[30:31]
	v_pk_fma_f32 v[28:29], v[138:139], v[28:29], v[6:7]
	v_pk_fma_f32 v[30:31], v[140:141], v[30:31], v[4:5]
	s_nop 0
	v_cvt_pk_bf16_f32 v30, v30, v31
	v_cvt_pk_bf16_f32 v31, v28, v29
	global_store_dwordx2 v[150:151], v[30:31], off
	v_readlane_b32 s4, v143, 22
	s_add_i32 s6, s0, 134
	s_lshl_b32 s6, s6, 12
	v_lshl_add_u64 v[148:149], v[136:137], 0, s[6:7]
	v_pk_mul_f32 v[32:33], v[32:33], s[4:5] op_sel_hi:[1,0]
	v_pk_mul_f32 v[34:35], v[34:35], s[4:5] op_sel_hi:[1,0]
	v_pk_mul_f32 v[32:33], v[2:3], v[32:33]
	v_pk_mul_f32 v[34:35], v[0:1], v[34:35]
	v_pk_fma_f32 v[32:33], v[138:139], v[32:33], v[6:7]
	v_pk_fma_f32 v[34:35], v[140:141], v[34:35], v[4:5]
	s_nop 0
	v_cvt_pk_bf16_f32 v34, v34, v35
	v_cvt_pk_bf16_f32 v35, v32, v33
	global_store_dwordx2 v[148:149], v[34:35], off
	v_readlane_b32 s4, v143, 23
	s_add_i32 s6, s0, 135
	s_lshl_b32 s6, s6, 12
	v_lshl_add_u64 v[150:151], v[136:137], 0, s[6:7]
	v_pk_mul_f32 v[36:37], v[36:37], s[4:5] op_sel_hi:[1,0]
	v_pk_mul_f32 v[38:39], v[38:39], s[4:5] op_sel_hi:[1,0]
	v_pk_mul_f32 v[36:37], v[2:3], v[36:37]
	v_pk_mul_f32 v[38:39], v[0:1], v[38:39]
	v_pk_fma_f32 v[36:37], v[138:139], v[36:37], v[6:7]
	v_pk_fma_f32 v[38:39], v[140:141], v[38:39], v[4:5]
	s_nop 0
	v_cvt_pk_bf16_f32 v38, v38, v39
	v_cvt_pk_bf16_f32 v39, v36, v37
	global_store_dwordx2 v[150:151], v[38:39], off
	v_readlane_b32 s4, v143, 24
	s_add_i32 s6, s0, 136
	s_lshl_b32 s6, s6, 12
	v_lshl_add_u64 v[148:149], v[136:137], 0, s[6:7]
	v_pk_mul_f32 v[40:41], v[40:41], s[4:5] op_sel_hi:[1,0]
	v_pk_mul_f32 v[42:43], v[42:43], s[4:5] op_sel_hi:[1,0]
	v_pk_mul_f32 v[40:41], v[2:3], v[40:41]
	v_pk_mul_f32 v[42:43], v[0:1], v[42:43]
	v_pk_fma_f32 v[40:41], v[138:139], v[40:41], v[6:7]
	v_pk_fma_f32 v[42:43], v[140:141], v[42:43], v[4:5]
	s_nop 0
	v_cvt_pk_bf16_f32 v42, v42, v43
	v_cvt_pk_bf16_f32 v43, v40, v41
	global_store_dwordx2 v[148:149], v[42:43], off
	v_readlane_b32 s4, v143, 25
	s_add_i32 s6, s0, 137
	s_lshl_b32 s6, s6, 12
	v_lshl_add_u64 v[150:151], v[136:137], 0, s[6:7]
	v_pk_mul_f32 v[44:45], v[44:45], s[4:5] op_sel_hi:[1,0]
	v_pk_mul_f32 v[46:47], v[46:47], s[4:5] op_sel_hi:[1,0]
	v_pk_mul_f32 v[44:45], v[2:3], v[44:45]
	v_pk_mul_f32 v[46:47], v[0:1], v[46:47]
	v_pk_fma_f32 v[44:45], v[138:139], v[44:45], v[6:7]
; __device__ __forceinline__ void st_bf4(bf16_t* p, f32x4 v) { u32x2 w; w.x = pk2(v[0], v[1]); w.y = pk2(v[2], v[3]); *(u32x2*)p = w; }
; __device__ __forceinline__ void xcd_barrier(const XcdBarrier& b) {
;     asm volatile("s_waitcnt vmcnt(0)" ::: "memory");
;     __syncthreads();
;     if (threadIdx.x == 0) {
;         unsigned* bar = b.bar;
;         __builtin_amdgcn_s_waitcnt(0);
;         unsigned nloc = b.st[0], nx = b.st[1];
;         if (nloc == 0u) { xcd_barrier_complete(bar, b.x, nloc, nx); b.st[0] = nloc; b.st[1] = nx; }
; __global__ void __launch_bounds__(NTHR, 2) fwd_kernel(Args a) {
;     ...
;               for (int j = 0; j < 16; ++j) { const int row = u.pm * BM + ai * HALF + wid2 * 16 + j; const float rstd = row_rstd(slots1, row);
;                   st_bf4(H2 + (size_t)row * DM + colg, (xr[ai][j] * rstd * gg) * sc + sh); }
	v_pk_fma_f32 v[46:47], v[140:141], v[46:47], v[4:5]
	s_nop 0
	v_cvt_pk_bf16_f32 v46, v46, v47
	v_cvt_pk_bf16_f32 v47, v44, v45
	global_store_dwordx2 v[150:151], v[46:47], off
	v_readlane_b32 s4, v143, 26
	s_add_i32 s6, s0, 138
	s_lshl_b32 s6, s6, 12
	v_lshl_add_u64 v[148:149], v[136:137], 0, s[6:7]
	v_pk_mul_f32 v[48:49], v[48:49], s[4:5] op_sel_hi:[1,0]
	v_pk_mul_f32 v[50:51], v[50:51], s[4:5] op_sel_hi:[1,0]
	v_pk_mul_f32 v[48:49], v[2:3], v[48:49]
	v_pk_mul_f32 v[50:51], v[0:1], v[50:51]
	v_pk_fma_f32 v[48:49], v[138:139], v[48:49], v[6:7]
	v_pk_fma_f32 v[50:51], v[140:141], v[50:51], v[4:5]
	s_nop 0
	v_cvt_pk_bf16_f32 v50, v50, v51
	v_cvt_pk_bf16_f32 v51, v48, v49
	global_store_dwordx2 v[148:149], v[50:51], off
	v_readlane_b32 s4, v143, 27
	s_add_i32 s6, s0, 139
	s_lshl_b32 s6, s6, 12
	v_lshl_add_u64 v[150:151], v[136:137], 0, s[6:7]
	v_pk_mul_f32 v[52:53], v[52:53], s[4:5] op_sel_hi:[1,0]
	v_pk_mul_f32 v[54:55], v[54:55], s[4:5] op_sel_hi:[1,0]
	v_pk_mul_f32 v[52:53], v[2:3], v[52:53]
	v_pk_mul_f32 v[54:55], v[0:1], v[54:55]
	v_pk_fma_f32 v[52:53], v[138:139], v[52:53], v[6:7]
	v_pk_fma_f32 v[54:55], v[140:141], v[54:55], v[4:5]
	s_nop 0
	v_cvt_pk_bf16_f32 v54, v54, v55
	v_cvt_pk_bf16_f32 v55, v52, v53
	global_store_dwordx2 v[150:151], v[54:55], off
	v_readlane_b32 s4, v143, 28
	s_add_i32 s6, s0, 140
	s_lshl_b32 s6, s6, 12
	v_lshl_add_u64 v[148:149], v[136:137], 0, s[6:7]
	v_pk_mul_f32 v[56:57], v[56:57], s[4:5] op_sel_hi:[1,0]
	v_pk_mul_f32 v[58:59], v[58:59], s[4:5] op_sel_hi:[1,0]
	v_pk_mul_f32 v[56:57], v[2:3], v[56:57]
	v_pk_mul_f32 v[58:59], v[0:1], v[58:59]
	v_pk_fma_f32 v[56:57], v[138:139], v[56:57], v[6:7]
	v_pk_fma_f32 v[58:59], v[140:141], v[58:59], v[4:5]
	s_nop 0
	v_cvt_pk_bf16_f32 v58, v58, v59
	v_cvt_pk_bf16_f32 v59, v56, v57
	global_store_dwordx2 v[148:149], v[58:59], off
	v_readlane_b32 s4, v143, 29
	s_add_i32 s6, s0, 141
	s_lshl_b32 s6, s6, 12
	v_lshl_add_u64 v[150:151], v[136:137], 0, s[6:7]
	v_pk_mul_f32 v[60:61], v[60:61], s[4:5] op_sel_hi:[1,0]
	v_pk_mul_f32 v[62:63], v[62:63], s[4:5] op_sel_hi:[1,0]
	v_pk_mul_f32 v[60:61], v[2:3], v[60:61]
	v_pk_mul_f32 v[62:63], v[0:1], v[62:63]
	v_pk_fma_f32 v[60:61], v[138:139], v[60:61], v[6:7]
	v_pk_fma_f32 v[62:63], v[140:141], v[62:63], v[4:5]
	s_nop 0
	v_cvt_pk_bf16_f32 v62, v62, v63
	v_cvt_pk_bf16_f32 v63, v60, v61
	global_store_dwordx2 v[150:151], v[62:63], off
	v_readlane_b32 s4, v143, 30
	s_add_i32 s6, s0, 142
	s_lshl_b32 s6, s6, 12
	v_lshl_add_u64 v[148:149], v[136:137], 0, s[6:7]
	v_pk_mul_f32 v[64:65], v[64:65], s[4:5] op_sel_hi:[1,0]
	v_pk_mul_f32 v[66:67], v[66:67], s[4:5] op_sel_hi:[1,0]
	v_pk_mul_f32 v[64:65], v[2:3], v[64:65]
	v_pk_mul_f32 v[66:67], v[0:1], v[66:67]
	v_pk_fma_f32 v[64:65], v[138:139], v[64:65], v[6:7]
	v_pk_fma_f32 v[66:67], v[140:141], v[66:67], v[4:5]
	s_nop 0
	v_cvt_pk_bf16_f32 v66, v66, v67
	v_cvt_pk_bf16_f32 v67, v64, v65
	global_store_dwordx2 v[148:149], v[66:67], off
	v_readlane_b32 s4, v143, 31
	s_add_i32 s6, s0, 143
	s_lshl_b32 s6, s6, 12
	v_lshl_add_u64 v[150:151], v[136:137], 0, s[6:7]
	v_pk_mul_f32 v[132:133], v[132:133], s[4:5] op_sel_hi:[1,0]
	v_pk_mul_f32 v[134:135], v[134:135], s[4:5] op_sel_hi:[1,0]
	v_pk_mul_f32 v[132:133], v[2:3], v[132:133]
	v_pk_mul_f32 v[134:135], v[0:1], v[134:135]
	v_pk_fma_f32 v[132:133], v[138:139], v[132:133], v[6:7]
	v_pk_fma_f32 v[134:135], v[140:141], v[134:135], v[4:5]
	s_nop 0
	v_cvt_pk_bf16_f32 v134, v134, v135
	v_cvt_pk_bf16_f32 v135, v132, v133
	global_store_dwordx2 v[150:151], v[134:135], off
	s_waitcnt vmcnt(0)
	s_barrier
	s_and_saveexec_b64 s[0:1], s[70:71]
	s_cbranch_execz .LBB0_1790
	s_add_i32 s2, 0, 0x20020
	v_mov_b32_e32 v0, s2
	s_waitcnt vmcnt(0) expcnt(0) lgkmcnt(0)
	ds_read_b32 v2, v0
	s_add_i32 s2, 0, 0x20024
	v_mov_b32_e32 v0, s2
	ds_read_b32 v0, v0
	s_waitcnt lgkmcnt(1)
	v_cmp_ne_u32_e32 vcc, 0, v2
	s_cbranch_vccnz .LBB0_1754
	v_readlane_b32 s2, v254, 0
	s_mul_i32 s33, s69, s2
	s_add_u32 s2, s66, 0x4200
	s_addc_u32 s3, s67, 0
	s_add_u32 s4, s66, 0x4400
	s_addc_u32 s5, s67, 0
	s_add_u32 s6, s66, 0x4500
	s_addc_u32 s7, s67, 0
	s_add_u32 s8, s66, 0x4600
	s_addc_u32 s9, s67, 0
	s_add_u32 s10, s66, 0x4700
	s_addc_u32 s11, s67, 0
	s_add_u32 s12, s66, 0x4800
	s_addc_u32 s13, s67, 0
	s_add_u32 s14, s66, 0x4900
	s_addc_u32 s15, s67, 0
	s_add_u32 s16, s66, 0x4a00
	s_addc_u32 s17, s67, 0
	s_add_u32 s18, s66, 0x4b00
	s_addc_u32 s19, s67, 0
	s_add_u32 s20, s66, 0x4c00
	s_addc_u32 s21, s67, 0
	s_add_u32 s22, s66, 0x4d00
	s_addc_u32 s23, s67, 0
	s_add_u32 s24, s66, 0x4e00
	s_addc_u32 s25, s67, 0
	s_add_u32 s26, s66, 0x4f00
	s_addc_u32 s27, s67, 0
	s_add_u32 s28, s66, 0x5000
	s_addc_u32 s29, s67, 0
	s_add_u32 s30, s66, 0x5100
	s_addc_u32 s31, s67, 0
	s_add_u32 s34, s66, 0x5200
	s_addc_u32 s35, s67, 0
	s_add_u32 s36, s66, 0x5300
	s_mul_i32 s33, s33, s68
	s_addc_u32 s37, s67, 0
	s_mov_b32 s44, 1
	v_mov_b32_e32 v16, 0
	s_branch .LBB0_1742

; #define LAS __attribute__((address_space(3)))
; __device__ __forceinline__ void transpose_item(const float* W, int K, int N, bf16_t* WT, int drow0, LAS float* scr, int k0, int n0, int lane) {
; #pragma unroll 8
;     for (int i = 0; i < 32; ++i) { const int kk = 2 * i + (lane >> 5); scr[kk * 33 + (lane & 31)] = W[(size_t)(k0 + kk) * N + n0 + (lane & 31)]; }
; __global__ void __launch_bounds__(NTHR, 2) fwd_kernel(Args a) {
;     ...
;         for (int r = (bx - 128) * 8 + wave; r < 88 * 64; r += (G - 128) * 8)
;             transpose_item(a.in[I_WDN], FF, DM, WdT, (r % 64) * 32, scr, (r / 64) * 64, (r % 64) * 32, lane);
.LBB0_1810:
	s_lshl_b32 s14, s13, 1
	s_lshl_b32 s15, s12, 1
	v_or_b32_e32 v46, s14, v1
	v_or_b32_e32 v47, s15, v0
	s_add_i32 s16, s14, 4
	s_add_i32 s17, s15, 4
	s_add_i32 s18, s14, 8
	s_add_i32 s19, s15, 8
	s_add_i32 s20, s14, 12
	s_add_i32 s21, s15, 12
	s_add_i32 s22, s14, 16
	s_add_i32 s23, s15, 16
	s_add_i32 s24, s14, 20
	s_add_i32 s25, s15, 20
	s_add_i32 s26, s14, 24
	s_add_i32 s27, s15, 24
	s_add_i32 s14, s14, 28
	s_add_i32 s15, s15, 28
	v_add_u32_e32 v16, s6, v47
	v_or_b32_e32 v48, s16, v1
	v_or_b32_e32 v49, s17, v0
	v_or_b32_e32 v50, s18, v1
	v_or_b32_e32 v51, s19, v0
	v_or_b32_e32 v52, s20, v1
	v_or_b32_e32 v53, s21, v0
	v_or_b32_e32 v54, s22, v1
	v_or_b32_e32 v55, s23, v0
	v_or_b32_e32 v56, s24, v1
	v_or_b32_e32 v57, s25, v0
	v_or_b32_e32 v58, s26, v1
	v_or_b32_e32 v59, s27, v0
	v_or_b32_e32 v60, s14, v1
	v_or_b32_e32 v61, s15, v0
	v_add_u32_e32 v14, s3, v46
	v_ashrrev_i32_e32 v17, 31, v16
	v_add_u32_e32 v18, s3, v48
	v_add_u32_e32 v20, s6, v49
	v_add_u32_e32 v22, s3, v50
	v_add_u32_e32 v24, s6, v51
	v_add_u32_e32 v26, s3, v52
	v_add_u32_e32 v28, s6, v53
	v_add_u32_e32 v30, s3, v54
	v_add_u32_e32 v32, s6, v55
	v_add_u32_e32 v34, s3, v56
	v_add_u32_e32 v36, s6, v57
	v_add_u32_e32 v38, s3, v58
	v_add_u32_e32 v40, s6, v59
	v_add_u32_e32 v42, s3, v60
	v_add_u32_e32 v44, s6, v61
	v_ashrrev_i32_e32 v15, 31, v14
	v_lshlrev_b64 v[16:17], 13, v[16:17]
	v_ashrrev_i32_e32 v21, 31, v20
	v_ashrrev_i32_e32 v19, 31, v18
	v_ashrrev_i32_e32 v25, 31, v24
	v_ashrrev_i32_e32 v23, 31, v22
	v_ashrrev_i32_e32 v29, 31, v28
	v_ashrrev_i32_e32 v27, 31, v26
	v_ashrrev_i32_e32 v33, 31, v32
	v_ashrrev_i32_e32 v31, 31, v30
	v_ashrrev_i32_e32 v37, 31, v36
	v_ashrrev_i32_e32 v35, 31, v34
	v_ashrrev_i32_e32 v41, 31, v40
	v_ashrrev_i32_e32 v39, 31, v38
	v_ashrrev_i32_e32 v45, 31, v44
	v_ashrrev_i32_e32 v43, 31, v42
	v_lshlrev_b64 v[14:15], 13, v[14:15]
	v_lshl_add_u64 v[16:17], v[8:9], 0, v[16:17]
	v_lshlrev_b64 v[18:19], 13, v[18:19]
	v_lshlrev_b64 v[20:21], 13, v[20:21]
	v_lshlrev_b64 v[22:23], 13, v[22:23]
	v_lshlrev_b64 v[24:25], 13, v[24:25]
	v_lshlrev_b64 v[26:27], 13, v[26:27]
	v_lshlrev_b64 v[28:29], 13, v[28:29]
	v_lshlrev_b64 v[30:31], 13, v[30:31]
	v_lshlrev_b64 v[32:33], 13, v[32:33]
	v_lshlrev_b64 v[34:35], 13, v[34:35]
	v_lshlrev_b64 v[36:37], 13, v[36:37]
	v_lshlrev_b64 v[38:39], 13, v[38:39]
	v_lshlrev_b64 v[40:41], 13, v[40:41]
	v_lshlrev_b64 v[42:43], 13, v[42:43]
	v_lshlrev_b64 v[44:45], 13, v[44:45]
	v_lshl_add_u64 v[14:15], v[8:9], 0, v[14:15]
	v_lshl_add_u64 v[20:21], v[8:9], 0, v[20:21]
	v_lshl_add_u64 v[18:19], v[8:9], 0, v[18:19]
	v_lshl_add_u64 v[24:25], v[8:9], 0, v[24:25]
	v_lshl_add_u64 v[22:23], v[8:9], 0, v[22:23]
	v_lshl_add_u64 v[28:29], v[8:9], 0, v[28:29]
	v_lshl_add_u64 v[26:27], v[8:9], 0, v[26:27]
	v_lshl_add_u64 v[32:33], v[8:9], 0, v[32:33]
	v_lshl_add_u64 v[30:31], v[8:9], 0, v[30:31]
	v_lshl_add_u64 v[36:37], v[8:9], 0, v[36:37]
	v_lshl_add_u64 v[34:35], v[8:9], 0, v[34:35]
	v_lshl_add_u64 v[40:41], v[8:9], 0, v[40:41]
	v_lshl_add_u64 v[38:39], v[8:9], 0, v[38:39]
	v_lshl_add_u64 v[44:45], v[8:9], 0, v[44:45]
	v_lshl_add_u64 v[42:43], v[8:9], 0, v[42:43]
	global_load_dword v62, v[16:17], off
	global_load_dword v63, v[14:15], off
	global_load_dword v64, v[20:21], off
	global_load_dword v65, v[18:19], off
	global_load_dword v66, v[24:25], off
	global_load_dword v67, v[22:23], off
	global_load_dword v68, v[28:29], off
	global_load_dword v69, v[26:27], off
	global_load_dword v70, v[32:33], off
	global_load_dword v71, v[30:31], off
	global_load_dword v72, v[36:37], off
	global_load_dword v73, v[34:35], off
	global_load_dword v74, v[40:41], off
	global_load_dword v75, v[38:39], off
	global_load_dword v76, v[44:45], off
	global_load_dword v77, v[42:43], off
	s_add_i32 s12, s12, 16
	s_add_i32 s13, s13, 16
	s_add_i32 s7, s7, -16
	v_mad_u64_u32 v[14:15], s[14:15], v47, s9, v[4:5]
	s_cmp_lg_u32 s7, 0
	v_mad_u64_u32 v[16:17], s[14:15], v46, s9, v[4:5]
	v_mad_u64_u32 v[18:19], s[14:15], v49, s9, v[4:5]
	v_mad_u64_u32 v[20:21], s[14:15], v48, s9, v[4:5]
	v_mad_u64_u32 v[22:23], s[14:15], v51, s9, v[4:5]
	v_mad_u64_u32 v[24:25], s[14:15], v50, s9, v[4:5]
	v_mad_u64_u32 v[26:27], s[14:15], v53, s9, v[4:5]
	v_mad_u64_u32 v[28:29], s[14:15], v52, s9, v[4:5]
	v_mad_u64_u32 v[30:31], s[14:15], v55, s9, v[4:5]
	v_mad_u64_u32 v[32:33], s[14:15], v54, s9, v[4:5]
	v_mad_u64_u32 v[34:35], s[14:15], v57, s9, v[4:5]
	v_mad_u64_u32 v[36:37], s[14:15], v56, s9, v[4:5]
	v_mad_u64_u32 v[38:39], s[14:15], v59, s9, v[4:5]
	v_mad_u64_u32 v[40:41], s[14:15], v58, s9, v[4:5]
	v_mad_u64_u32 v[42:43], s[14:15], v61, s9, v[4:5]
	v_mad_u64_u32 v[44:45], s[14:15], v60, s9, v[4:5]
	s_waitcnt vmcnt(15)
	ds_write_b32 v14, v62
	s_waitcnt vmcnt(14)
	ds_write_b32 v16, v63
	s_waitcnt vmcnt(13)
	ds_write_b32 v18, v64
	s_waitcnt vmcnt(12)
	ds_write_b32 v20, v65
	s_waitcnt vmcnt(11)
	ds_write_b32 v22, v66
	s_waitcnt vmcnt(10)
	ds_write_b32 v24, v67
	s_waitcnt vmcnt(9)
	ds_write_b32 v26, v68
	s_waitcnt vmcnt(8)
	ds_write_b32 v28, v69
	s_waitcnt vmcnt(7)
	ds_write_b32 v30, v70
	s_waitcnt vmcnt(6)
	ds_write_b32 v32, v71
	s_waitcnt vmcnt(5)
	ds_write_b32 v34, v72
	s_waitcnt vmcnt(4)
	ds_write_b32 v36, v73
	s_waitcnt vmcnt(3)
	ds_write_b32 v38, v74
	s_waitcnt vmcnt(2)
	ds_write_b32 v40, v75
	s_waitcnt vmcnt(1)
	ds_write_b32 v42, v76
	s_waitcnt vmcnt(0)
	ds_write_b32 v44, v77
	s_cbranch_scc1 .LBB0_1810
; #define LAS __attribute__((address_space(3)))
; __device__ __forceinline__ unsigned pk2(float lo, float hi) { return pk2hw(lo, hi); }
; __device__ __forceinline__ void transpose_item(const float* W, int K, int N, bf16_t* WT, int drow0, LAS float* scr, int k0, int n0, int lane) {
;     ...
;     asm volatile("s_waitcnt lgkmcnt(0)" ::: "memory");
;     const int c = lane & 7;
; #pragma unroll
;     for (int j = 0; j < 4; ++j) { const int n = (lane >> 3) + 8 * j; const LAS float* s = scr + (8 * c) * 33 + n;
;         u32x4 o; o.x = pk2(s[0 * 33], s[1 * 33]); o.y = pk2(s[2 * 33], s[3 * 33]); o.z = pk2(s[4 * 33], s[5 * 33]); o.w = pk2(s[6 * 33], s[7 * 33]);
;         *(u32x4*)(WT + (size_t)(drow0 + n) * K + k0 + 8 * c) = o; }
;     asm volatile("s_waitcnt lgkmcnt(0)" ::: "memory");
; __global__ void __launch_bounds__(NTHR, 2) fwd_kernel(Args a) {
;     ...
;         for (int r = (bx - 128) * 8 + wave; r < 88 * 64; r += (G - 128) * 8)
;             transpose_item(a.in[I_WDN], FF, DM, WdT, (r % 64) * 32, scr, (r / 64) * 64, (r % 64) * 32, lane);
	s_waitcnt lgkmcnt(0)
	ds_read2_b32 v[8:9], v10 offset0:33 offset1:41
	ds_read2_b32 v[18:19], v10 offset1:8
	ds_read2_b32 v[20:21], v10 offset0:66 offset1:74
	ds_read2_b32 v[22:23], v10 offset0:99 offset1:107
	ds_read2_b32 v[24:25], v10 offset0:132 offset1:140
	ds_read2_b32 v[26:27], v10 offset0:165 offset1:173
	ds_read2_b32 v[28:29], v10 offset0:198 offset1:206
	ds_read2_b32 v[30:31], v10 offset0:231 offset1:239
	s_waitcnt lgkmcnt(6)
	v_cvt_pk_bf16_f32 v14, v18, v8
	v_or_b32_e32 v8, s2, v5
	s_ashr_i32 s7, s6, 31
	v_mul_lo_u32 v34, v8, s11
	v_lshl_add_u64 v[32:33], s[6:7], 1, v[6:7]
	v_ashrrev_i32_e32 v35, 31, v34
	s_waitcnt lgkmcnt(4)
	v_cvt_pk_bf16_f32 v15, v20, v22
	s_waitcnt lgkmcnt(2)
	v_cvt_pk_bf16_f32 v16, v24, v26
	s_waitcnt lgkmcnt(0)
	v_cvt_pk_bf16_f32 v17, v28, v30
	v_lshl_add_u64 v[34:35], v[34:35], 1, v[32:33]
	v_or_b32_e32 v8, s2, v11
	global_store_dwordx4 v[34:35], v[14:17], off sc1
	v_mul_lo_u32 v8, v8, s11
	s_add_i32 s8, s10, s8
	v_cvt_pk_bf16_f32 v14, v19, v9
	v_cvt_pk_bf16_f32 v15, v21, v23
	v_cvt_pk_bf16_f32 v16, v25, v27
	v_cvt_pk_bf16_f32 v17, v29, v31
	v_ashrrev_i32_e32 v9, 31, v8
	ds_read2_b32 v[18:19], v10 offset0:49 offset1:57
	ds_read2_b32 v[20:21], v10 offset0:16 offset1:24
	ds_read2_b32 v[22:23], v10 offset0:82 offset1:90
	ds_read2_b32 v[24:25], v10 offset0:115 offset1:123
	ds_read2_b32 v[26:27], v10 offset0:148 offset1:156
	ds_read2_b32 v[28:29], v10 offset0:181 offset1:189
	ds_read2_b32 v[30:31], v10 offset0:214 offset1:222
	ds_read2_b32 v[34:35], v10 offset0:247 offset1:255
	v_lshl_add_u64 v[8:9], v[8:9], 1, v[32:33]
	global_store_dwordx4 v[8:9], v[14:17], off sc1
	v_or_b32_e32 v8, s2, v12
	v_mul_lo_u32 v8, v8, s11
	v_ashrrev_i32_e32 v9, 31, v8
	s_waitcnt lgkmcnt(6)
	v_cvt_pk_bf16_f32 v14, v20, v18
	s_waitcnt lgkmcnt(4)
	v_cvt_pk_bf16_f32 v15, v22, v24
	s_waitcnt lgkmcnt(2)
	v_cvt_pk_bf16_f32 v16, v26, v28
	s_waitcnt lgkmcnt(0)
	v_cvt_pk_bf16_f32 v17, v30, v34
	v_lshl_add_u64 v[8:9], v[8:9], 1, v[32:33]
	global_store_dwordx4 v[8:9], v[14:17], off sc1
	v_or_b32_e32 v8, s2, v13
	v_mul_lo_u32 v8, v8, s11
	v_ashrrev_i32_e32 v9, 31, v8
	v_cvt_pk_bf16_f32 v14, v21, v19
	v_cvt_pk_bf16_f32 v15, v23, v25
	v_cvt_pk_bf16_f32 v16, v27, v29
	v_cvt_pk_bf16_f32 v17, v31, v35
	v_lshl_add_u64 v[8:9], v[8:9], 1, v[32:33]
	global_store_dwordx4 v[8:9], v[14:17], off sc1
	s_waitcnt lgkmcnt(0)
	s_cmpk_lt_i32 s8, 0x1600
	s_cbranch_scc1 .LBB0_1809

; __device__ __forceinline__ float row_rstd(const float* slots, int row) {
;     const unsigned long long* sp = (const unsigned long long*)(slots + (size_t)row * 8); float t = 0.f;
; #pragma unroll
;     for (int q = 0; q < 4; ++q) { const unsigned long long w = __hip_atomic_load(sp + q, __ATOMIC_RELAXED, __HIP_MEMORY_SCOPE_AGENT); t += __uint_as_float((unsigned)w) + __uint_as_float((unsigned)(w >> 32)); }
;     return rsqrtf(t * (1.0f / DM) + EPS);
; }
; __global__ void __launch_bounds__(NTHR, 2) fwd_kernel(Args a) {
;     ...
;         { const int wid2 = __builtin_amdgcn_readfirstlane(tid2 >> 6), colg = u.pn * BM + 4 * (tid2 & 63);
;           const f32x4 gf = *(const f32x4*)(a.in[I_GF] + colg);
; #pragma unroll
;           for (int ai = 0; ai < 2; ++ai)
; #pragma unroll
;               for (int j = 0; j < 16; ++j) { const int row = u.pm * BM + ai * HALF + wid2 * 16 + j; const float rstd = row_rstd(slots2, row);
;                   *(f32x4*)(out + (size_t)row * DM + colg) = xr[ai][j] * rstd * gf; }
.LBB0_2009:
	s_or_b64 exec, exec, s[0:1]
	s_waitcnt lgkmcnt(0)
	s_barrier
	v_readfirstlane_b32 s0, v189
	s_ashr_i32 s0, s0, 2
	v_lshlrev_b32_e32 v0, 2, v189
	s_and_b32 s0, s0, -16
	v_and_b32_e32 v0, 0xfc, v0
	s_add_i32 s0, s0, s46
	v_or_b32_e32 v0, s45, v0
	v_ashrrev_i32_e32 v1, 31, v0
	v_lshlrev_b64 v[64:65], 2, v[0:1]
	v_lshl_add_u64 v[0:1], s[62:63], 0, v[64:65]
	global_load_dwordx4 v[0:3], v[0:1], off
	v_lshl_add_u64 v[64:65], s[64:65], 0, v[64:65]
	s_mov_b32 s4, s33
	s_mov_b32 s5, s44
	v_and_b32_e32 v144, 31, v189
	v_and_b32_e32 v145, 15, v144
	v_lshrrev_b32_e32 v144, 4, v144
	v_lshl_add_u32 v145, v144, 7, v145
	v_add_u32_e32 v145, s0, v145
	v_lshlrev_b32_e32 v66, 5, v145
	global_load_dwordx4 v[136:139], v66, s[4:5] sc1
	global_load_dwordx4 v[140:143], v66, s[4:5] offset:16 sc1
	v_mov_b32_e32 v67, 0x358637bd
	s_mov_b32 s2, 0x800000
	s_waitcnt vmcnt(0)
	v_add_f32_e32 v136, v136, v137
	v_add_f32_e32 v137, v138, v139
	v_add_f32_e32 v136, 0, v136
	v_add_f32_e32 v138, v140, v141
	v_add_f32_e32 v136, v136, v137
	v_add_f32_e32 v139, v142, v143
	v_add_f32_e32 v136, v136, v138
	v_add_f32_e32 v136, v136, v139
	v_fmamk_f32 v136, v136, 0x3a000000, v67
	v_mul_f32_e32 v137, 0x4b800000, v136
	v_cmp_gt_f32_e32 vcc, s2, v136
	s_nop 1
	v_cndmask_b32_e32 v136, v136, v137, vcc
	v_rsq_f32_e32 v136, v136
	s_nop 0
	v_mul_f32_e32 v137, 0x45800000, v136
	v_cndmask_b32_e32 v66, v136, v137, vcc
	s_mov_b32 s7, 0
	v_readlane_b32 s4, v66, 0
	s_add_i32 s6, s0, 0
	s_lshl_b32 s6, s6, 13
	v_lshl_add_u64 v[144:145], v[64:65], 0, s[6:7]
	v_pk_mul_f32 v[136:137], v[72:73], s[4:5] op_sel_hi:[1,0]
	v_pk_mul_f32 v[138:139], v[68:69], s[4:5] op_sel_hi:[1,0]
	v_pk_mul_f32 v[136:137], v[0:1], v[136:137]
	v_pk_mul_f32 v[138:139], v[2:3], v[138:139]
	global_store_dwordx4 v[144:145], v[136:139], off
	v_readlane_b32 s4, v66, 1
	s_add_i32 s6, s0, 1
	s_lshl_b32 s6, s6, 13
	v_lshl_add_u64 v[146:147], v[64:65], 0, s[6:7]
	v_pk_mul_f32 v[140:141], v[76:77], s[4:5] op_sel_hi:[1,0]
	v_pk_mul_f32 v[142:143], v[70:71], s[4:5] op_sel_hi:[1,0]
	v_pk_mul_f32 v[140:141], v[0:1], v[140:141]
	v_pk_mul_f32 v[142:143], v[2:3], v[142:143]
	global_store_dwordx4 v[146:147], v[140:143], off
	v_readlane_b32 s4, v66, 2
	s_add_i32 s6, s0, 2
	s_lshl_b32 s6, s6, 13
	v_lshl_add_u64 v[144:145], v[64:65], 0, s[6:7]
	v_pk_mul_f32 v[136:137], v[80:81], s[4:5] op_sel_hi:[1,0]
	v_pk_mul_f32 v[138:139], v[74:75], s[4:5] op_sel_hi:[1,0]
	v_pk_mul_f32 v[136:137], v[0:1], v[136:137]
	v_pk_mul_f32 v[138:139], v[2:3], v[138:139]
	global_store_dwordx4 v[144:145], v[136:139], off
	v_readlane_b32 s4, v66, 3
	s_add_i32 s6, s0, 3
	s_lshl_b32 s6, s6, 13
	v_lshl_add_u64 v[146:147], v[64:65], 0, s[6:7]
	v_pk_mul_f32 v[140:141], v[86:87], s[4:5] op_sel_hi:[1,0]
	v_pk_mul_f32 v[142:143], v[78:79], s[4:5] op_sel_hi:[1,0]
	v_pk_mul_f32 v[140:141], v[0:1], v[140:141]
	v_pk_mul_f32 v[142:143], v[2:3], v[142:143]
	global_store_dwordx4 v[146:147], v[140:143], off
	v_readlane_b32 s4, v66, 4
	s_add_i32 s6, s0, 4
	s_lshl_b32 s6, s6, 13
	v_lshl_add_u64 v[144:145], v[64:65], 0, s[6:7]
	v_pk_mul_f32 v[136:137], v[90:91], s[4:5] op_sel_hi:[1,0]
	v_pk_mul_f32 v[138:139], v[82:83], s[4:5] op_sel_hi:[1,0]
	v_pk_mul_f32 v[136:137], v[0:1], v[136:137]
	v_pk_mul_f32 v[138:139], v[2:3], v[138:139]
	global_store_dwordx4 v[144:145], v[136:139], off
	v_readlane_b32 s4, v66, 5
	s_add_i32 s6, s0, 5
	s_lshl_b32 s6, s6, 13
	v_lshl_add_u64 v[146:147], v[64:65], 0, s[6:7]
	v_pk_mul_f32 v[140:141], v[94:95], s[4:5] op_sel_hi:[1,0]
	v_pk_mul_f32 v[142:143], v[84:85], s[4:5] op_sel_hi:[1,0]
	v_pk_mul_f32 v[140:141], v[0:1], v[140:141]
	v_pk_mul_f32 v[142:143], v[2:3], v[142:143]
	global_store_dwordx4 v[146:147], v[140:143], off
	v_readlane_b32 s4, v66, 6
	s_add_i32 s6, s0, 6
	s_lshl_b32 s6, s6, 13
	v_lshl_add_u64 v[144:145], v[64:65], 0, s[6:7]
	v_pk_mul_f32 v[136:137], v[98:99], s[4:5] op_sel_hi:[1,0]
	v_pk_mul_f32 v[138:139], v[88:89], s[4:5] op_sel_hi:[1,0]
	v_pk_mul_f32 v[136:137], v[0:1], v[136:137]
	v_pk_mul_f32 v[138:139], v[2:3], v[138:139]
	global_store_dwordx4 v[144:145], v[136:139], off
	v_readlane_b32 s4, v66, 7
	s_add_i32 s6, s0, 7
	s_lshl_b32 s6, s6, 13
	v_lshl_add_u64 v[146:147], v[64:65], 0, s[6:7]
	v_pk_mul_f32 v[140:141], v[102:103], s[4:5] op_sel_hi:[1,0]
	v_pk_mul_f32 v[142:143], v[92:93], s[4:5] op_sel_hi:[1,0]
	v_pk_mul_f32 v[140:141], v[0:1], v[140:141]
	v_pk_mul_f32 v[142:143], v[2:3], v[142:143]
	global_store_dwordx4 v[146:147], v[140:143], off
	v_readlane_b32 s4, v66, 8
	s_add_i32 s6, s0, 8
	s_lshl_b32 s6, s6, 13
	v_lshl_add_u64 v[144:145], v[64:65], 0, s[6:7]
	v_pk_mul_f32 v[136:137], v[106:107], s[4:5] op_sel_hi:[1,0]
	v_pk_mul_f32 v[138:139], v[96:97], s[4:5] op_sel_hi:[1,0]
	v_pk_mul_f32 v[136:137], v[0:1], v[136:137]
	v_pk_mul_f32 v[138:139], v[2:3], v[138:139]
	global_store_dwordx4 v[144:145], v[136:139], off
	v_readlane_b32 s4, v66, 9
	s_add_i32 s6, s0, 9
	s_lshl_b32 s6, s6, 13
	v_lshl_add_u64 v[146:147], v[64:65], 0, s[6:7]
	v_pk_mul_f32 v[140:141], v[110:111], s[4:5] op_sel_hi:[1,0]
	v_pk_mul_f32 v[142:143], v[100:101], s[4:5] op_sel_hi:[1,0]
	v_pk_mul_f32 v[140:141], v[0:1], v[140:141]
	v_pk_mul_f32 v[142:143], v[2:3], v[142:143]
	global_store_dwordx4 v[146:147], v[140:143], off
	v_readlane_b32 s4, v66, 10
	s_add_i32 s6, s0, 10
	s_lshl_b32 s6, s6, 13
	v_lshl_add_u64 v[144:145], v[64:65], 0, s[6:7]
	v_pk_mul_f32 v[136:137], v[114:115], s[4:5] op_sel_hi:[1,0]
	v_pk_mul_f32 v[138:139], v[104:105], s[4:5] op_sel_hi:[1,0]
	v_pk_mul_f32 v[136:137], v[0:1], v[136:137]
	v_pk_mul_f32 v[138:139], v[2:3], v[138:139]
	global_store_dwordx4 v[144:145], v[136:139], off
	v_readlane_b32 s4, v66, 11
	s_add_i32 s6, s0, 11
	s_lshl_b32 s6, s6, 13
; __global__ void __launch_bounds__(NTHR, 2) fwd_kernel(Args a) {
;     ...
;           for (int ai = 0; ai < 2; ++ai)
; #pragma unroll
;               for (int j = 0; j < 16; ++j) { const int row = u.pm * BM + ai * HALF + wid2 * 16 + j; const float rstd = row_rstd(slots2, row);
;                   *(f32x4*)(out + (size_t)row * DM + colg) = xr[ai][j] * rstd * gf; }
	v_lshl_add_u64 v[146:147], v[64:65], 0, s[6:7]
	v_pk_mul_f32 v[140:141], v[118:119], s[4:5] op_sel_hi:[1,0]
	v_pk_mul_f32 v[142:143], v[108:109], s[4:5] op_sel_hi:[1,0]
	v_pk_mul_f32 v[140:141], v[0:1], v[140:141]
	v_pk_mul_f32 v[142:143], v[2:3], v[142:143]
	global_store_dwordx4 v[146:147], v[140:143], off
	v_readlane_b32 s4, v66, 12
	s_add_i32 s6, s0, 12
	s_lshl_b32 s6, s6, 13
	v_lshl_add_u64 v[144:145], v[64:65], 0, s[6:7]
	v_pk_mul_f32 v[136:137], v[122:123], s[4:5] op_sel_hi:[1,0]
	v_pk_mul_f32 v[138:139], v[112:113], s[4:5] op_sel_hi:[1,0]
	v_pk_mul_f32 v[136:137], v[0:1], v[136:137]
	v_pk_mul_f32 v[138:139], v[2:3], v[138:139]
	global_store_dwordx4 v[144:145], v[136:139], off
	v_readlane_b32 s4, v66, 13
	s_add_i32 s6, s0, 13
	s_lshl_b32 s6, s6, 13
	v_lshl_add_u64 v[146:147], v[64:65], 0, s[6:7]
	v_pk_mul_f32 v[140:141], v[126:127], s[4:5] op_sel_hi:[1,0]
	v_pk_mul_f32 v[142:143], v[116:117], s[4:5] op_sel_hi:[1,0]
	v_pk_mul_f32 v[140:141], v[0:1], v[140:141]
	v_pk_mul_f32 v[142:143], v[2:3], v[142:143]
	global_store_dwordx4 v[146:147], v[140:143], off
	v_readlane_b32 s4, v66, 14
	s_add_i32 s6, s0, 14
	s_lshl_b32 s6, s6, 13
	v_lshl_add_u64 v[144:145], v[64:65], 0, s[6:7]
	v_pk_mul_f32 v[136:137], v[128:129], s[4:5] op_sel_hi:[1,0]
	v_pk_mul_f32 v[138:139], v[120:121], s[4:5] op_sel_hi:[1,0]
	v_pk_mul_f32 v[136:137], v[0:1], v[136:137]
	v_pk_mul_f32 v[138:139], v[2:3], v[138:139]
	global_store_dwordx4 v[144:145], v[136:139], off
	v_readlane_b32 s4, v66, 15
	s_add_i32 s6, s0, 15
	s_lshl_b32 s6, s6, 13
	v_lshl_add_u64 v[146:147], v[64:65], 0, s[6:7]
	v_pk_mul_f32 v[140:141], v[130:131], s[4:5] op_sel_hi:[1,0]
	v_pk_mul_f32 v[142:143], v[124:125], s[4:5] op_sel_hi:[1,0]
	v_pk_mul_f32 v[140:141], v[0:1], v[140:141]
	v_pk_mul_f32 v[142:143], v[2:3], v[142:143]
	global_store_dwordx4 v[146:147], v[140:143], off
	v_readlane_b32 s4, v66, 16
	s_add_i32 s6, s0, 128
	s_lshl_b32 s6, s6, 13
	v_lshl_add_u64 v[144:145], v[64:65], 0, s[6:7]
	v_pk_mul_f32 v[136:137], v[134:135], s[4:5] op_sel_hi:[1,0]
	v_pk_mul_f32 v[138:139], v[132:133], s[4:5] op_sel_hi:[1,0]
	v_pk_mul_f32 v[136:137], v[0:1], v[136:137]
	v_pk_mul_f32 v[138:139], v[2:3], v[138:139]
	global_store_dwordx4 v[144:145], v[136:139], off
	v_readlane_b32 s4, v66, 17
	s_add_i32 s6, s0, 129
	s_lshl_b32 s6, s6, 13
	v_lshl_add_u64 v[146:147], v[64:65], 0, s[6:7]
	v_pk_mul_f32 v[140:141], v[62:63], s[4:5] op_sel_hi:[1,0]
	v_pk_mul_f32 v[142:143], v[60:61], s[4:5] op_sel_hi:[1,0]
	v_pk_mul_f32 v[140:141], v[0:1], v[140:141]
	v_pk_mul_f32 v[142:143], v[2:3], v[142:143]
	global_store_dwordx4 v[146:147], v[140:143], off
	v_readlane_b32 s4, v66, 18
	s_add_i32 s6, s0, 130
	s_lshl_b32 s6, s6, 13
	v_lshl_add_u64 v[144:145], v[64:65], 0, s[6:7]
	v_pk_mul_f32 v[136:137], v[58:59], s[4:5] op_sel_hi:[1,0]
	v_pk_mul_f32 v[138:139], v[56:57], s[4:5] op_sel_hi:[1,0]
	v_pk_mul_f32 v[136:137], v[0:1], v[136:137]
	v_pk_mul_f32 v[138:139], v[2:3], v[138:139]
	global_store_dwordx4 v[144:145], v[136:139], off
	v_readlane_b32 s4, v66, 19
	s_add_i32 s6, s0, 131
	s_lshl_b32 s6, s6, 13
	v_lshl_add_u64 v[146:147], v[64:65], 0, s[6:7]
	v_pk_mul_f32 v[140:141], v[54:55], s[4:5] op_sel_hi:[1,0]
	v_pk_mul_f32 v[142:143], v[52:53], s[4:5] op_sel_hi:[1,0]
	v_pk_mul_f32 v[140:141], v[0:1], v[140:141]
	v_pk_mul_f32 v[142:143], v[2:3], v[142:143]
	global_store_dwordx4 v[146:147], v[140:143], off
	v_readlane_b32 s4, v66, 20
	s_add_i32 s6, s0, 132
	s_lshl_b32 s6, s6, 13
	v_lshl_add_u64 v[144:145], v[64:65], 0, s[6:7]
	v_pk_mul_f32 v[136:137], v[50:51], s[4:5] op_sel_hi:[1,0]
	v_pk_mul_f32 v[138:139], v[48:49], s[4:5] op_sel_hi:[1,0]
	v_pk_mul_f32 v[136:137], v[0:1], v[136:137]
	v_pk_mul_f32 v[138:139], v[2:3], v[138:139]
	global_store_dwordx4 v[144:145], v[136:139], off
	v_readlane_b32 s4, v66, 21
	s_add_i32 s6, s0, 133
	s_lshl_b32 s6, s6, 13
	v_lshl_add_u64 v[146:147], v[64:65], 0, s[6:7]
	v_pk_mul_f32 v[140:141], v[46:47], s[4:5] op_sel_hi:[1,0]
	v_pk_mul_f32 v[142:143], v[44:45], s[4:5] op_sel_hi:[1,0]
; __global__ void __launch_bounds__(NTHR, 2) fwd_kernel(Args a) {
;     ...
;           for (int ai = 0; ai < 2; ++ai)
; #pragma unroll
;               for (int j = 0; j < 16; ++j) { const int row = u.pm * BM + ai * HALF + wid2 * 16 + j; const float rstd = row_rstd(slots2, row);
;                   *(f32x4*)(out + (size_t)row * DM + colg) = xr[ai][j] * rstd * gf; }
	v_pk_mul_f32 v[140:141], v[0:1], v[140:141]
	v_pk_mul_f32 v[142:143], v[2:3], v[142:143]
	global_store_dwordx4 v[146:147], v[140:143], off
	v_readlane_b32 s4, v66, 22
	s_add_i32 s6, s0, 134
	s_lshl_b32 s6, s6, 13
	v_lshl_add_u64 v[144:145], v[64:65], 0, s[6:7]
	v_pk_mul_f32 v[136:137], v[42:43], s[4:5] op_sel_hi:[1,0]
	v_pk_mul_f32 v[138:139], v[40:41], s[4:5] op_sel_hi:[1,0]
	v_pk_mul_f32 v[136:137], v[0:1], v[136:137]
	v_pk_mul_f32 v[138:139], v[2:3], v[138:139]
	global_store_dwordx4 v[144:145], v[136:139], off
	v_readlane_b32 s4, v66, 23
	s_add_i32 s6, s0, 135
	s_lshl_b32 s6, s6, 13
	v_lshl_add_u64 v[146:147], v[64:65], 0, s[6:7]
	v_pk_mul_f32 v[140:141], v[38:39], s[4:5] op_sel_hi:[1,0]
	v_pk_mul_f32 v[142:143], v[36:37], s[4:5] op_sel_hi:[1,0]
	v_pk_mul_f32 v[140:141], v[0:1], v[140:141]
	v_pk_mul_f32 v[142:143], v[2:3], v[142:143]
	global_store_dwordx4 v[146:147], v[140:143], off
	v_readlane_b32 s4, v66, 24
	s_add_i32 s6, s0, 136
	s_lshl_b32 s6, s6, 13
	v_lshl_add_u64 v[144:145], v[64:65], 0, s[6:7]
	v_pk_mul_f32 v[136:137], v[34:35], s[4:5] op_sel_hi:[1,0]
	v_pk_mul_f32 v[138:139], v[32:33], s[4:5] op_sel_hi:[1,0]
	v_pk_mul_f32 v[136:137], v[0:1], v[136:137]
	v_pk_mul_f32 v[138:139], v[2:3], v[138:139]
	global_store_dwordx4 v[144:145], v[136:139], off
	v_readlane_b32 s4, v66, 25
	s_add_i32 s6, s0, 137
	s_lshl_b32 s6, s6, 13
	v_lshl_add_u64 v[146:147], v[64:65], 0, s[6:7]
	v_pk_mul_f32 v[140:141], v[30:31], s[4:5] op_sel_hi:[1,0]
	v_pk_mul_f32 v[142:143], v[28:29], s[4:5] op_sel_hi:[1,0]
	v_pk_mul_f32 v[140:141], v[0:1], v[140:141]
	v_pk_mul_f32 v[142:143], v[2:3], v[142:143]
	global_store_dwordx4 v[146:147], v[140:143], off
	v_readlane_b32 s4, v66, 26
	s_add_i32 s6, s0, 138
	s_lshl_b32 s6, s6, 13
	v_lshl_add_u64 v[144:145], v[64:65], 0, s[6:7]
	v_pk_mul_f32 v[136:137], v[26:27], s[4:5] op_sel_hi:[1,0]
	v_pk_mul_f32 v[138:139], v[24:25], s[4:5] op_sel_hi:[1,0]
	v_pk_mul_f32 v[136:137], v[0:1], v[136:137]
	v_pk_mul_f32 v[138:139], v[2:3], v[138:139]
	global_store_dwordx4 v[144:145], v[136:139], off
	v_readlane_b32 s4, v66, 27
	s_add_i32 s6, s0, 139
	s_lshl_b32 s6, s6, 13
	v_lshl_add_u64 v[146:147], v[64:65], 0, s[6:7]
	v_pk_mul_f32 v[140:141], v[22:23], s[4:5] op_sel_hi:[1,0]
	v_pk_mul_f32 v[142:143], v[20:21], s[4:5] op_sel_hi:[1,0]
	v_pk_mul_f32 v[140:141], v[0:1], v[140:141]
	v_pk_mul_f32 v[142:143], v[2:3], v[142:143]
	global_store_dwordx4 v[146:147], v[140:143], off
	v_readlane_b32 s4, v66, 28
	s_add_i32 s6, s0, 140
	s_lshl_b32 s6, s6, 13
	v_lshl_add_u64 v[144:145], v[64:65], 0, s[6:7]
	v_pk_mul_f32 v[136:137], v[18:19], s[4:5] op_sel_hi:[1,0]
	v_pk_mul_f32 v[138:139], v[14:15], s[4:5] op_sel_hi:[1,0]
	v_pk_mul_f32 v[136:137], v[0:1], v[136:137]
	v_pk_mul_f32 v[138:139], v[2:3], v[138:139]
	global_store_dwordx4 v[144:145], v[136:139], off
	v_readlane_b32 s4, v66, 29
	s_add_i32 s6, s0, 141
	s_lshl_b32 s6, s6, 13
	v_lshl_add_u64 v[146:147], v[64:65], 0, s[6:7]
	v_pk_mul_f32 v[140:141], v[12:13], s[4:5] op_sel_hi:[1,0]
	v_pk_mul_f32 v[142:143], v[8:9], s[4:5] op_sel_hi:[1,0]
	v_pk_mul_f32 v[140:141], v[0:1], v[140:141]
	v_pk_mul_f32 v[142:143], v[2:3], v[142:143]
	global_store_dwordx4 v[146:147], v[140:143], off
	v_readlane_b32 s4, v66, 30
	s_add_i32 s6, s0, 142
	s_lshl_b32 s6, s6, 13
	v_lshl_add_u64 v[144:145], v[64:65], 0, s[6:7]
	v_pk_mul_f32 v[136:137], v[6:7], s[4:5] op_sel_hi:[1,0]
	v_pk_mul_f32 v[138:139], v[4:5], s[4:5] op_sel_hi:[1,0]
	v_pk_mul_f32 v[136:137], v[0:1], v[136:137]
	v_pk_mul_f32 v[138:139], v[2:3], v[138:139]
	global_store_dwordx4 v[144:145], v[136:139], off
	v_readlane_b32 s4, v66, 31
	s_add_i32 s6, s0, 143
	s_lshl_b32 s6, s6, 13
	v_lshl_add_u64 v[146:147], v[64:65], 0, s[6:7]
	v_pk_mul_f32 v[140:141], v[16:17], s[4:5] op_sel_hi:[1,0]
	v_pk_mul_f32 v[142:143], v[10:11], s[4:5] op_sel_hi:[1,0]
	v_pk_mul_f32 v[140:141], v[0:1], v[140:141]
	v_pk_mul_f32 v[142:143], v[2:3], v[142:143]
	global_store_dwordx4 v[146:147], v[140:143], off
	s_endpgm
